# input-GEMM phase work distribution: u2 units of the last two rounds on WGs 0..191 / 0..127, conv units 3 per WG on WGs 192..255 (started after the u1 rounds) and 1 on WGs 128..191
# speedup vs baseline: 1.0067x; 1.0054x over previous
.LBB0_777:
	s_add_i32 s34, s34, 1
	s_cmp_ge_i32 s34, s24
	s_mov_b64 s[50:51], -1
	s_cbranch_scc0 .LBB0_780
	s_sub_i32 s1, s34, s24
	v_readlane_b32 s4, v249, 37
	v_readlane_b32 s6, v249, 2
	s_mul_i32 s4, s1, s4
	s_mul_hi_u32 s5, s1, s6
	s_add_i32 s5, s5, s4
	s_mul_i32 s1, s1, s6
	s_add_u32 s52, s1, s61
	v_readlane_b32 s1, v249, 36
	s_addc_u32 s53, s5, s1
	s_sub_i32 s4, s34, s24
	s_lshl_b32 s5, s4, 6
	s_sub_u32 s52, s52, s5
	s_subb_u32 s53, s53, 0
	s_cmp_lg_u32 s4, 0
	s_cbranch_scc1 .Lk0s_ok
	s_cmpk_lt_u32 s61, 0xc0
	s_cbranch_scc1 .Lk0s_ok
	s_movk_i32 s52, 0x1000
.Lk0s_ok:
	v_cmp_gt_i64_e32 vcc, s[52:53], v[220:221]
	s_mov_b64 s[50:51], 0
	s_mov_b64 s[58:59], 0
	s_mov_b32 s4, s16
	s_mov_b32 s1, s14
	s_cbranch_vccnz .LBB0_780
	s_ashr_i32 s1, s52, 31
	s_lshr_b32 s1, s1, 29
	s_add_i32 s1, s52, s1
	s_ashr_i32 s4, s1, 3
	s_and_b32 s1, s1, -8
	s_sub_i32 s1, s52, s1
	s_cmp_lt_i32 s1, 0
	s_cselect_b32 s5, 41, 40
	s_mul_i32 s1, s1, s5
	s_add_i32 s1, s1, s4
	s_mul_hi_i32 s4, s1, 0x66666667
	s_lshr_b32 s5, s4, 31
	s_ashr_i32 s4, s4, 4
	s_add_i32 s4, s4, s5
	s_lshl_b32 s5, s4, 3
	s_sub_i32 s6, 64, s5
	s_min_i32 s6, s6, 8
	s_abs_i32 s7, s6
	v_cvt_f32_u32_e32 v0, s7
	s_sub_i32 s9, 0, s7
	s_mul_i32 s4, s4, 40
	s_sub_i32 s4, s1, s4
	v_rcp_iflag_f32_e32 v0, v0
	s_abs_i32 s1, s4
	s_xor_b32 s8, s4, s6
	s_ashr_i32 s8, s8, 31
	v_mul_f32_e32 v0, 0x4f7ffffe, v0
	v_cvt_u32_f32_e32 v0, v0
	s_mov_b64 s[58:59], -1
	v_readfirstlane_b32 s10, v0
	s_mul_i32 s9, s9, s10
	s_mul_hi_u32 s9, s10, s9
	s_add_i32 s10, s10, s9
	s_mul_hi_u32 s9, s1, s10
	s_mul_i32 s10, s9, s7
	s_sub_i32 s1, s1, s10
	s_add_i32 s11, s9, 1
	s_sub_i32 s10, s1, s7
	s_cmp_ge_u32 s1, s7
	s_cselect_b32 s9, s11, s9
	s_cselect_b32 s1, s10, s1
	s_add_i32 s10, s9, 1
	s_cmp_ge_u32 s1, s7
	s_cselect_b32 s1, s10, s9
	s_xor_b32 s1, s1, s8
	s_sub_i32 s1, s1, s8
	s_mul_i32 s6, s1, s6
	s_sub_i32 s4, s4, s6
	s_add_i32 s4, s5, s4

.LBB0_809:
	s_cmpk_lt_u32 s61, 0x80
	s_cbranch_scc1 .LBB0_867
	v_cmp_eq_u32_e32 vcc, 0, v225
	s_and_saveexec_b64 s[0:1], vcc
	s_cbranch_execz .LBB0_815
	global_load_dword v0, v65, s[2:3] sc1
	s_waitcnt vmcnt(0)
	v_cmp_le_u32_e32 vcc, s85, v0
	s_cbranch_vccnz .LBB0_814
	s_mov_b32 s4, 0

.LBB0_815:
	s_or_b64 exec, exec, s[0:1]
	v_readlane_b32 s0, v252, 22
	v_readlane_b32 s1, v252, 23
	s_andn2_b64 vcc, exec, s[0:1]
	s_waitcnt lgkmcnt(0)
	s_barrier
	s_cbranch_vccnz .LBB0_859
	v_readlane_b32 s0, v250, 5
	v_readlane_b32 s1, v250, 6
	s_mov_b32 s22, s0
	v_readlane_b32 s4, v255, 0
	s_mul_i32 s1, s22, 0x7c00
	v_readlane_b32 s6, v255, 2
	s_mul_hi_i32 s0, s0, 0x7c00
	v_readlane_b32 s7, v255, 3
	s_add_u32 s2, s6, s1
	s_addc_u32 s3, s7, s0
	v_lshlrev_b32_sdwa v64, v246, v225 dst_sel:DWORD dst_unused:UNUSED_PAD src0_sel:DWORD src1_sel:BYTE_0
	s_waitcnt vmcnt(6)
	v_lshl_add_u64 v[0:1], s[2:3], 0, v[64:65]
	global_load_dword v53, v64, s[2:3]
	global_load_dword v54, v64, s[2:3] offset:1024
	global_load_dword v55, v64, s[2:3] offset:2048
	global_load_dword v56, v64, s[2:3] offset:3072
	s_movk_i32 s2, 0x1000
	v_add_co_u32_e32 v2, vcc, s2, v0
	s_movk_i32 s2, 0x2000
	s_nop 0
	v_addc_co_u32_e32 v3, vcc, 0, v1, vcc
	v_add_co_u32_e32 v4, vcc, s2, v0
	s_movk_i32 s2, 0x3000
	s_nop 0
	v_addc_co_u32_e32 v5, vcc, 0, v1, vcc
	global_load_dword v57, v[4:5], off offset:-4096
	global_load_dword v58, v[2:3], off offset:1024
	global_load_dword v59, v[2:3], off offset:2048
	global_load_dword v60, v[2:3], off offset:3072
	global_load_dword v61, v[4:5], off
	global_load_dword v62, v[4:5], off offset:1024
	global_load_dword v63, v[4:5], off offset:2048
	global_load_dword v66, v[4:5], off offset:3072
	v_add_co_u32_e32 v2, vcc, s2, v0
	s_movk_i32 s2, 0x4000
	s_nop 0
	v_addc_co_u32_e32 v3, vcc, 0, v1, vcc
	v_add_co_u32_e32 v4, vcc, s2, v0
	s_movk_i32 s2, 0x5000
	s_nop 0
	v_addc_co_u32_e32 v5, vcc, 0, v1, vcc
	global_load_dword v67, v[4:5], off offset:-4096
	global_load_dword v68, v[2:3], off offset:1024
	global_load_dword v69, v[2:3], off offset:2048
	global_load_dword v70, v[2:3], off offset:3072
	global_load_dword v71, v[4:5], off
	global_load_dword v72, v[4:5], off offset:1024
	global_load_dword v73, v[4:5], off offset:2048
	global_load_dword v74, v[4:5], off offset:3072
	v_add_co_u32_e32 v2, vcc, s2, v0
	s_movk_i32 s2, 0x6000
	s_nop 0
	v_addc_co_u32_e32 v3, vcc, 0, v1, vcc
	v_add_co_u32_e32 v4, vcc, s2, v0
	s_lshl_b32 s0, s22, 8
	s_nop 0
	v_addc_co_u32_e32 v5, vcc, 0, v1, vcc
	global_load_dword v75, v[4:5], off offset:-4096
	global_load_dword v76, v[2:3], off offset:1024
	global_load_dword v77, v[2:3], off offset:2048
	global_load_dword v78, v[2:3], off offset:3072
	global_load_dword v79, v[4:5], off
	global_load_dword v80, v[4:5], off offset:1024
	global_load_dword v81, v[4:5], off offset:2048
	global_load_dword v82, v[4:5], off offset:3072
	s_ashr_i32 s1, s0, 31
	s_movk_i32 s2, 0x7000
	v_readlane_b32 s8, v255, 4
	v_add_co_u32_e32 v0, vcc, s2, v0
	s_lshl_b64 s[0:1], s[0:1], 2
	v_readlane_b32 s9, v255, 5
	v_addc_co_u32_e32 v1, vcc, 0, v1, vcc
	s_add_u32 s2, s8, s0
	global_load_dword v83, v[0:1], off
	global_load_dword v84, v[0:1], off offset:1024
	global_load_dword v85, v[0:1], off offset:2048
	s_addc_u32 s3, s9, s1
	global_load_dword v86, v64, s[2:3]
	v_readlane_b32 s10, v255, 6
	v_readlane_b32 s11, v255, 7
	s_add_u32 s22, s10, s0
	v_readlane_b32 s12, v255, 8
	s_addc_u32 s23, s11, s1
	v_readlane_b32 s13, v255, 9
	s_add_u32 s2, s12, s0
	s_addc_u32 s3, s13, s1
	s_add_i32 s67, s61, 64
	s_cmpk_ge_u32 s61, 0xc0
	s_cselect_b32 s0, 0x100, 0
	s_sub_i32 s67, s67, s0
	s_lshl_b32 s0, s67, 6
	s_movk_i32 s10, 64
	v_readlane_b32 s8, v249, 38
	s_add_i32 s34, s0, -15
	s_lshl_b32 s13, s10, 6
	v_readlane_b32 s9, v249, 39
	v_readlane_b32 s5, v255, 1
	v_readlane_b32 s14, v255, 10
	v_readlane_b32 s15, v255, 11
	v_readlane_b32 s16, v255, 12
	v_readlane_b32 s17, v255, 13
	v_readlane_b32 s18, v255, 14
	v_readlane_b32 s19, v255, 15
	s_branch .LBB0_819

.LBB0_818:
	s_or_b64 exec, exec, s[0:1]
	s_waitcnt vmcnt(9)
	v_ashrrev_i32_e32 v35, 8, v50
	s_waitcnt vmcnt(1)
	v_lshlrev_b32_e32 v0, 14, v35
	v_lshlrev_b32_sdwa v1, v236, v50 dst_sel:DWORD dst_unused:UNUSED_PAD src0_sel:DWORD src1_sel:BYTE_0
	v_add3_u32 v34, 0, v0, v1
	s_waitcnt lgkmcnt(0)
	s_barrier
	ds_read_u16 v0, v34
	ds_read_u16 v1, v34 offset:16384
	ds_read_u16 v2, v34 offset:16896
	v_lshlrev_b32_e32 v35, 15, v35
	v_lshlrev_b32_sdwa v87, v246, v50 dst_sel:DWORD dst_unused:UNUSED_PAD src0_sel:DWORD src1_sel:BYTE_0
	s_waitcnt lgkmcnt(2)
	v_lshlrev_b32_e32 v97, 16, v0
	ds_read_u16 v0, v34 offset:512
	ds_read_u16 v3, v34 offset:17408
	v_fma_f32 v97, v53, v97, v86
	s_waitcnt lgkmcnt(3)
	v_lshlrev_b32_e32 v1, 16, v1
	s_waitcnt lgkmcnt(2)
	v_lshlrev_b32_e32 v2, 16, v2
	s_waitcnt lgkmcnt(1)
	v_lshlrev_b32_e32 v96, 16, v0
	ds_read_u16 v0, v34 offset:1024
	s_waitcnt vmcnt(0)
	ds_read_u16 v4, v34 offset:17920
	v_fmac_f32_e32 v97, v54, v96
	v_fma_f32 v96, v53, v96, v86
	ds_read_u16 v5, v34 offset:18432
	s_waitcnt lgkmcnt(2)
	v_lshlrev_b32_e32 v95, 16, v0
	ds_read_u16 v0, v34 offset:1536
	v_fmac_f32_e32 v97, v55, v95
	v_fmac_f32_e32 v96, v54, v95
	ds_read_u16 v6, v34 offset:18944
	v_fma_f32 v95, v53, v95, v86
	s_waitcnt lgkmcnt(1)
	v_lshlrev_b32_e32 v94, 16, v0
	ds_read_u16 v0, v34 offset:2048
	v_fmac_f32_e32 v97, v56, v94
	ds_read_u16 v7, v34 offset:19456
	v_fmac_f32_e32 v96, v55, v94
	v_fmac_f32_e32 v95, v54, v94
	s_waitcnt lgkmcnt(1)
	v_lshlrev_b32_e32 v93, 16, v0
	ds_read_u16 v0, v34 offset:2560
	ds_read_u16 v9, v34 offset:19968
	v_fma_f32 v94, v53, v94, v86
	v_fmac_f32_e32 v97, v57, v93
	v_fmac_f32_e32 v96, v56, v93
	s_waitcnt lgkmcnt(1)
	v_lshlrev_b32_e32 v92, 16, v0
	ds_read_u16 v0, v34 offset:3072
	ds_read_u16 v10, v34 offset:20480
	v_fmac_f32_e32 v95, v55, v93
	v_fmac_f32_e32 v94, v54, v93
	v_fma_f32 v93, v53, v93, v86
	s_waitcnt lgkmcnt(1)
	v_lshlrev_b32_e32 v91, 16, v0
	ds_read_u16 v0, v34 offset:3584
	ds_read_u16 v11, v34 offset:20992
	v_fmac_f32_e32 v97, v58, v92
	v_fmac_f32_e32 v96, v57, v92
	ds_read_u16 v12, v34 offset:21504
	s_waitcnt lgkmcnt(2)
	v_lshlrev_b32_e32 v90, 16, v0
	ds_read_u16 v0, v34 offset:4096
	v_fmac_f32_e32 v95, v56, v92
	v_fmac_f32_e32 v94, v55, v92
	ds_read_u16 v13, v34 offset:22016
	v_fmac_f32_e32 v93, v54, v92
	s_waitcnt lgkmcnt(1)
	v_lshlrev_b32_e32 v89, 16, v0
	ds_read_u16 v0, v34 offset:4608
	v_fma_f32 v92, v53, v92, v86
	ds_read_u16 v14, v34 offset:22528
	v_fmac_f32_e32 v97, v59, v91
	v_fmac_f32_e32 v96, v58, v91
	s_waitcnt lgkmcnt(1)
	v_lshlrev_b32_e32 v88, 16, v0
	ds_read_u16 v0, v34 offset:5120
	ds_read_u16 v15, v34 offset:23040
	v_fmac_f32_e32 v95, v57, v91
	v_fmac_f32_e32 v94, v56, v91
	v_fmac_f32_e32 v93, v55, v91
	s_waitcnt lgkmcnt(1)
	v_lshlrev_b32_e32 v64, 16, v0
	ds_read_u16 v0, v34 offset:5632
	ds_read_u16 v16, v34 offset:23552
	v_fmac_f32_e32 v92, v54, v91
	v_fma_f32 v91, v53, v91, v86
	v_fmac_f32_e32 v97, v60, v90
	s_waitcnt lgkmcnt(1)
	v_lshlrev_b32_e32 v52, 16, v0
	ds_read_u16 v0, v34 offset:6144
	ds_read_u16 v18, v34 offset:24064
	v_fmac_f32_e32 v96, v59, v90
	v_fmac_f32_e32 v95, v58, v90
	ds_read_u16 v19, v34 offset:24576
	s_waitcnt lgkmcnt(2)
	v_lshlrev_b32_e32 v51, 16, v0
	ds_read_u16 v0, v34 offset:6656
	v_fmac_f32_e32 v94, v57, v90
	v_fmac_f32_e32 v93, v56, v90
	ds_read_u16 v20, v34 offset:25088
	v_fmac_f32_e32 v92, v55, v90
	s_waitcnt lgkmcnt(1)
	v_lshlrev_b32_e32 v49, 16, v0
	ds_read_u16 v0, v34 offset:7168
	v_fmac_f32_e32 v91, v54, v90
	ds_read_u16 v21, v34 offset:25600
	v_fma_f32 v90, v53, v90, v86
	v_fmac_f32_e32 v97, v61, v89
	s_waitcnt lgkmcnt(1)
	v_lshlrev_b32_e32 v48, 16, v0
	ds_read_u16 v0, v34 offset:7680
	ds_read_u16 v22, v34 offset:26112
	v_fmac_f32_e32 v96, v60, v89
	v_fmac_f32_e32 v95, v59, v89
	v_fmac_f32_e32 v94, v58, v89
	s_waitcnt lgkmcnt(1)
	v_lshlrev_b32_e32 v47, 16, v0
	ds_read_u16 v0, v34 offset:8192
	ds_read_u16 v23, v34 offset:26624
	v_fmac_f32_e32 v93, v57, v89
	v_fmac_f32_e32 v92, v56, v89
	v_fmac_f32_e32 v91, v55, v89
	s_waitcnt lgkmcnt(1)
	v_lshlrev_b32_e32 v46, 16, v0
	ds_read_u16 v0, v34 offset:8704
	ds_read_u16 v24, v34 offset:27136
	v_fmac_f32_e32 v90, v54, v89
	v_fma_f32 v89, v53, v89, v86
	ds_read_u16 v25, v34 offset:27648
	s_waitcnt lgkmcnt(2)
	v_lshlrev_b32_e32 v45, 16, v0
	ds_read_u16 v0, v34 offset:9216
	v_fmac_f32_e32 v97, v62, v88
	v_fmac_f32_e32 v96, v61, v88
	ds_read_u16 v27, v34 offset:28160
	v_fmac_f32_e32 v95, v60, v88
	s_waitcnt lgkmcnt(1)
	v_lshlrev_b32_e32 v44, 16, v0
	ds_read_u16 v0, v34 offset:9728
	v_fmac_f32_e32 v94, v59, v88
	ds_read_u16 v28, v34 offset:28672
	v_fmac_f32_e32 v93, v58, v88
	v_fmac_f32_e32 v92, v57, v88
	s_waitcnt lgkmcnt(1)
	v_lshlrev_b32_e32 v43, 16, v0
	ds_read_u16 v0, v34 offset:10240
	ds_read_u16 v29, v34 offset:29184
	v_fmac_f32_e32 v91, v56, v88
	v_fmac_f32_e32 v90, v55, v88
	v_fmac_f32_e32 v89, v54, v88
	s_waitcnt lgkmcnt(1)
	v_lshlrev_b32_e32 v42, 16, v0
	ds_read_u16 v0, v34 offset:10752
	ds_read_u16 v30, v34 offset:29696
	v_fma_f32 v88, v53, v88, v86
	v_fmac_f32_e32 v97, v63, v64
	v_fmac_f32_e32 v96, v62, v64
	s_waitcnt lgkmcnt(1)
	v_lshlrev_b32_e32 v41, 16, v0
	ds_read_u16 v0, v34 offset:11264
	ds_read_u16 v31, v34 offset:30208
	v_fmac_f32_e32 v95, v61, v64
	v_fmac_f32_e32 v94, v60, v64
	v_fmac_f32_e32 v93, v59, v64
	s_waitcnt lgkmcnt(1)
	v_lshlrev_b32_e32 v40, 16, v0
	ds_read_u16 v0, v34 offset:11776
	v_fmac_f32_e32 v92, v58, v64
	v_fmac_f32_e32 v91, v57, v64
	v_fmac_f32_e32 v90, v56, v64
	v_fmac_f32_e32 v89, v55, v64
	s_waitcnt lgkmcnt(0)
	v_lshlrev_b32_e32 v39, 16, v0
	ds_read_u16 v0, v34 offset:12288
	v_fmac_f32_e32 v88, v54, v64
	v_fma_f32 v64, v53, v64, v86
	v_fmac_f32_e32 v97, v66, v52
	v_fmac_f32_e32 v96, v63, v52
	s_waitcnt lgkmcnt(0)
	v_lshlrev_b32_e32 v38, 16, v0
	ds_read_u16 v0, v34 offset:12800
	v_fmac_f32_e32 v95, v62, v52
	v_fmac_f32_e32 v94, v61, v52
	v_fmac_f32_e32 v93, v60, v52
	v_fmac_f32_e32 v92, v59, v52
	s_waitcnt lgkmcnt(0)
	v_lshlrev_b32_e32 v37, 16, v0
	ds_read_u16 v0, v34 offset:13312
	v_fmac_f32_e32 v91, v58, v52
	v_fmac_f32_e32 v90, v57, v52
	v_fmac_f32_e32 v89, v56, v52
	v_fmac_f32_e32 v88, v55, v52
	s_waitcnt lgkmcnt(0)
	v_lshlrev_b32_e32 v36, 16, v0
	ds_read_u16 v0, v34 offset:13824
	v_fmac_f32_e32 v64, v54, v52
	v_fma_f32 v52, v53, v52, v86
	v_fmac_f32_e32 v97, v67, v51
	v_fmac_f32_e32 v96, v66, v51
	s_waitcnt lgkmcnt(0)
	v_lshlrev_b32_e32 v33, 16, v0
	ds_read_u16 v0, v34 offset:14336
	ds_read_u16 v32, v34 offset:30720
	v_fmac_f32_e32 v95, v63, v51
	v_fmac_f32_e32 v94, v62, v51
	v_fmac_f32_e32 v93, v61, v51
	v_fmac_f32_e32 v92, v60, v51
	v_fmac_f32_e32 v91, v59, v51
	v_fmac_f32_e32 v90, v58, v51
	v_fmac_f32_e32 v89, v57, v51
	v_fmac_f32_e32 v88, v56, v51
	v_fmac_f32_e32 v64, v55, v51
	v_fmac_f32_e32 v52, v54, v51
	v_fma_f32 v51, v53, v51, v86
	v_fmac_f32_e32 v97, v68, v49
	v_fmac_f32_e32 v96, v67, v49
	v_fmac_f32_e32 v95, v66, v49
	v_fmac_f32_e32 v94, v63, v49
	v_fmac_f32_e32 v93, v62, v49
	v_fmac_f32_e32 v92, v61, v49
	v_fmac_f32_e32 v91, v60, v49
	v_fmac_f32_e32 v90, v59, v49
	v_fmac_f32_e32 v89, v58, v49
	v_fmac_f32_e32 v88, v57, v49
	v_fmac_f32_e32 v64, v56, v49
	v_fmac_f32_e32 v52, v55, v49
	v_fmac_f32_e32 v51, v54, v49
	v_fma_f32 v49, v53, v49, v86
	v_fmac_f32_e32 v97, v69, v48
	v_fmac_f32_e32 v96, v68, v48
	v_fmac_f32_e32 v95, v67, v48
	v_fmac_f32_e32 v94, v66, v48
	v_fmac_f32_e32 v93, v63, v48
	v_fmac_f32_e32 v92, v62, v48
	v_fmac_f32_e32 v91, v61, v48
	v_fmac_f32_e32 v90, v60, v48
	v_fmac_f32_e32 v89, v59, v48
	v_fmac_f32_e32 v88, v58, v48
	v_fmac_f32_e32 v64, v57, v48
	v_fmac_f32_e32 v52, v56, v48
	v_fmac_f32_e32 v51, v55, v48
	v_fmac_f32_e32 v49, v54, v48
	v_fma_f32 v48, v53, v48, v86
	s_waitcnt lgkmcnt(1)
	v_lshlrev_b32_e32 v26, 16, v0
	ds_read_u16 v0, v34 offset:14848
	v_fmac_f32_e32 v97, v70, v47
	v_fmac_f32_e32 v96, v69, v47
	v_fmac_f32_e32 v95, v68, v47
	v_fmac_f32_e32 v94, v67, v47
	v_fmac_f32_e32 v93, v66, v47
	v_fmac_f32_e32 v92, v63, v47
	v_fmac_f32_e32 v91, v62, v47
	v_fmac_f32_e32 v90, v61, v47
	v_fmac_f32_e32 v89, v60, v47
	v_fmac_f32_e32 v88, v59, v47
	v_fmac_f32_e32 v64, v58, v47
	v_fmac_f32_e32 v52, v57, v47
	v_fmac_f32_e32 v51, v56, v47
	v_fmac_f32_e32 v49, v55, v47
	v_fmac_f32_e32 v48, v54, v47
	v_fma_f32 v47, v53, v47, v86
	v_fmac_f32_e32 v97, v71, v46
	v_fmac_f32_e32 v96, v70, v46
	v_fmac_f32_e32 v95, v69, v46
	v_fmac_f32_e32 v94, v68, v46
	v_fmac_f32_e32 v93, v67, v46
	v_fmac_f32_e32 v92, v66, v46
	v_fmac_f32_e32 v91, v63, v46
	v_fmac_f32_e32 v90, v62, v46
	v_fmac_f32_e32 v89, v61, v46
	v_fmac_f32_e32 v88, v60, v46
	v_fmac_f32_e32 v64, v59, v46
	v_fmac_f32_e32 v52, v58, v46
	v_fmac_f32_e32 v51, v57, v46
	v_fmac_f32_e32 v49, v56, v46
	v_fmac_f32_e32 v48, v55, v46
	v_fmac_f32_e32 v47, v54, v46
	v_fma_f32 v46, v53, v46, v86
	v_fmac_f32_e32 v97, v72, v45
	v_fmac_f32_e32 v96, v71, v45
	v_fmac_f32_e32 v95, v70, v45
	v_fmac_f32_e32 v94, v69, v45
	v_fmac_f32_e32 v93, v68, v45
	v_fmac_f32_e32 v92, v67, v45
	v_fmac_f32_e32 v91, v66, v45
	v_fmac_f32_e32 v90, v63, v45
	v_fmac_f32_e32 v89, v62, v45
	v_fmac_f32_e32 v88, v61, v45
	v_fmac_f32_e32 v64, v60, v45
	v_fmac_f32_e32 v52, v59, v45
	v_fmac_f32_e32 v51, v58, v45
	v_fmac_f32_e32 v49, v57, v45
	v_fmac_f32_e32 v48, v56, v45
	v_fmac_f32_e32 v47, v55, v45
	v_fmac_f32_e32 v46, v54, v45
	v_fma_f32 v45, v53, v45, v86
	v_fmac_f32_e32 v97, v73, v44
	v_fmac_f32_e32 v96, v72, v44
	v_fmac_f32_e32 v95, v71, v44
	v_fmac_f32_e32 v94, v70, v44
	v_fmac_f32_e32 v93, v69, v44
	v_fmac_f32_e32 v92, v68, v44
	v_fmac_f32_e32 v91, v67, v44
	v_fmac_f32_e32 v90, v66, v44
	v_fmac_f32_e32 v89, v63, v44
	v_fmac_f32_e32 v88, v62, v44
	v_fmac_f32_e32 v64, v61, v44
	v_fmac_f32_e32 v52, v60, v44
	v_fmac_f32_e32 v51, v59, v44
	v_fmac_f32_e32 v49, v58, v44
	v_fmac_f32_e32 v48, v57, v44
	v_fmac_f32_e32 v47, v56, v44
	v_fmac_f32_e32 v46, v55, v44
	v_fmac_f32_e32 v45, v54, v44
	v_fma_f32 v44, v53, v44, v86
	v_fmac_f32_e32 v97, v74, v43
	v_fmac_f32_e32 v96, v73, v43
	v_fmac_f32_e32 v95, v72, v43
	v_fmac_f32_e32 v94, v71, v43
	v_fmac_f32_e32 v93, v70, v43
	v_fmac_f32_e32 v92, v69, v43
	v_fmac_f32_e32 v91, v68, v43
	v_fmac_f32_e32 v90, v67, v43
	v_fmac_f32_e32 v89, v66, v43
	v_fmac_f32_e32 v88, v63, v43
	v_fmac_f32_e32 v64, v62, v43
	v_fmac_f32_e32 v52, v61, v43
	v_fmac_f32_e32 v51, v60, v43
	v_fmac_f32_e32 v49, v59, v43
	v_fmac_f32_e32 v48, v58, v43
	v_fmac_f32_e32 v47, v57, v43
	v_fmac_f32_e32 v46, v56, v43
	v_fmac_f32_e32 v45, v55, v43
	v_fmac_f32_e32 v44, v54, v43
	v_fma_f32 v43, v53, v43, v86
	s_waitcnt lgkmcnt(0)
	v_lshlrev_b32_e32 v17, 16, v0
	ds_read_u16 v0, v34 offset:15360
	v_fmac_f32_e32 v97, v75, v42
	v_fmac_f32_e32 v96, v74, v42
	v_fmac_f32_e32 v95, v73, v42
	v_fmac_f32_e32 v94, v72, v42
	v_fmac_f32_e32 v93, v71, v42
	v_fmac_f32_e32 v92, v70, v42
	v_fmac_f32_e32 v91, v69, v42
	v_fmac_f32_e32 v90, v68, v42
	v_fmac_f32_e32 v89, v67, v42
	v_fmac_f32_e32 v88, v66, v42
	v_fmac_f32_e32 v64, v63, v42
	v_fmac_f32_e32 v52, v62, v42
	v_fmac_f32_e32 v51, v61, v42
	v_fmac_f32_e32 v49, v60, v42
	v_fmac_f32_e32 v48, v59, v42
	v_fmac_f32_e32 v47, v58, v42
	v_fmac_f32_e32 v46, v57, v42
	v_fmac_f32_e32 v45, v56, v42
	v_fmac_f32_e32 v44, v55, v42
	v_fmac_f32_e32 v43, v54, v42
	v_fma_f32 v42, v53, v42, v86
	v_fmac_f32_e32 v97, v76, v41
	v_fmac_f32_e32 v96, v75, v41
	v_fmac_f32_e32 v95, v74, v41
	v_fmac_f32_e32 v94, v73, v41
	v_fmac_f32_e32 v93, v72, v41
	v_fmac_f32_e32 v92, v71, v41
	v_fmac_f32_e32 v91, v70, v41
	v_fmac_f32_e32 v90, v69, v41
	v_fmac_f32_e32 v89, v68, v41
	v_fmac_f32_e32 v88, v67, v41
	v_fmac_f32_e32 v64, v66, v41
	v_fmac_f32_e32 v52, v63, v41
	v_fmac_f32_e32 v51, v62, v41
	v_fmac_f32_e32 v49, v61, v41
	v_fmac_f32_e32 v48, v60, v41
	v_fmac_f32_e32 v47, v59, v41
	v_fmac_f32_e32 v46, v58, v41
	v_fmac_f32_e32 v45, v57, v41
	v_fmac_f32_e32 v44, v56, v41
	v_fmac_f32_e32 v43, v55, v41
	v_fmac_f32_e32 v42, v54, v41
	v_fma_f32 v41, v53, v41, v86
	v_fmac_f32_e32 v97, v77, v40
	v_fmac_f32_e32 v96, v76, v40
	v_fmac_f32_e32 v95, v75, v40
	v_fmac_f32_e32 v94, v74, v40
	v_fmac_f32_e32 v93, v73, v40
	v_fmac_f32_e32 v92, v72, v40
	v_fmac_f32_e32 v91, v71, v40
	v_fmac_f32_e32 v90, v70, v40
	v_fmac_f32_e32 v89, v69, v40
	v_fmac_f32_e32 v88, v68, v40
	v_fmac_f32_e32 v64, v67, v40
	v_fmac_f32_e32 v52, v66, v40
	v_fmac_f32_e32 v51, v63, v40
	v_fmac_f32_e32 v49, v62, v40
	v_fmac_f32_e32 v48, v61, v40
	v_fmac_f32_e32 v47, v60, v40
	v_fmac_f32_e32 v46, v59, v40
	v_fmac_f32_e32 v45, v58, v40
	v_fmac_f32_e32 v44, v57, v40
	v_fmac_f32_e32 v43, v56, v40
	v_fmac_f32_e32 v42, v55, v40
	v_fmac_f32_e32 v41, v54, v40
	v_fma_f32 v40, v53, v40, v86
	v_fmac_f32_e32 v97, v78, v39
	v_fmac_f32_e32 v96, v77, v39
	v_fmac_f32_e32 v95, v76, v39
	v_fmac_f32_e32 v94, v75, v39
	v_fmac_f32_e32 v93, v74, v39
	v_fmac_f32_e32 v92, v73, v39
	v_fmac_f32_e32 v91, v72, v39
	v_fmac_f32_e32 v90, v71, v39
	v_fmac_f32_e32 v89, v70, v39
	v_fmac_f32_e32 v88, v69, v39
	v_fmac_f32_e32 v64, v68, v39
	v_fmac_f32_e32 v52, v67, v39
	v_fmac_f32_e32 v51, v66, v39
	v_fmac_f32_e32 v49, v63, v39
	v_fmac_f32_e32 v48, v62, v39
	v_fmac_f32_e32 v47, v61, v39
	v_fmac_f32_e32 v46, v60, v39
	v_fmac_f32_e32 v45, v59, v39
	v_fmac_f32_e32 v44, v58, v39
	v_fmac_f32_e32 v43, v57, v39
	v_fmac_f32_e32 v42, v56, v39
	v_fmac_f32_e32 v41, v55, v39
	v_fmac_f32_e32 v40, v54, v39
	v_fma_f32 v39, v53, v39, v86
	v_fmac_f32_e32 v97, v79, v38
	v_fmac_f32_e32 v96, v78, v38
	v_fmac_f32_e32 v95, v77, v38
	v_fmac_f32_e32 v94, v76, v38
	v_fmac_f32_e32 v93, v75, v38
	v_fmac_f32_e32 v92, v74, v38
	v_fmac_f32_e32 v91, v73, v38
	v_fmac_f32_e32 v90, v72, v38
	v_fmac_f32_e32 v89, v71, v38
	v_fmac_f32_e32 v88, v70, v38
	v_fmac_f32_e32 v64, v69, v38
	v_fmac_f32_e32 v52, v68, v38
	v_fmac_f32_e32 v51, v67, v38
	v_fmac_f32_e32 v49, v66, v38
	v_fmac_f32_e32 v48, v63, v38
	v_fmac_f32_e32 v47, v62, v38
	v_fmac_f32_e32 v46, v61, v38
	v_fmac_f32_e32 v45, v60, v38
	v_fmac_f32_e32 v44, v59, v38
	v_fmac_f32_e32 v43, v58, v38
	v_fmac_f32_e32 v42, v57, v38
	v_fmac_f32_e32 v41, v56, v38
	v_fmac_f32_e32 v40, v55, v38
	v_fmac_f32_e32 v39, v54, v38
	v_fma_f32 v38, v53, v38, v86
	s_waitcnt lgkmcnt(0)
	v_lshlrev_b32_e32 v8, 16, v0
	ds_read_u16 v0, v34 offset:15872
	v_fmac_f32_e32 v97, v80, v37
	v_fmac_f32_e32 v96, v79, v37
	v_fmac_f32_e32 v95, v78, v37
	v_fmac_f32_e32 v94, v77, v37
	v_fmac_f32_e32 v93, v76, v37
	v_fmac_f32_e32 v92, v75, v37
	v_fmac_f32_e32 v91, v74, v37
	v_fmac_f32_e32 v90, v73, v37
	v_fmac_f32_e32 v89, v72, v37
	v_fmac_f32_e32 v88, v71, v37
	v_fmac_f32_e32 v64, v70, v37
	v_fmac_f32_e32 v52, v69, v37
	v_fmac_f32_e32 v51, v68, v37
	v_fmac_f32_e32 v49, v67, v37
	v_fmac_f32_e32 v48, v66, v37
	v_fmac_f32_e32 v47, v63, v37
	v_fmac_f32_e32 v46, v62, v37
	v_fmac_f32_e32 v45, v61, v37
	v_fmac_f32_e32 v44, v60, v37
	v_fmac_f32_e32 v43, v59, v37
	v_fmac_f32_e32 v42, v58, v37
	v_fmac_f32_e32 v41, v57, v37
	v_fmac_f32_e32 v40, v56, v37
	v_fmac_f32_e32 v39, v55, v37
	v_fmac_f32_e32 v38, v54, v37
	v_fma_f32 v37, v53, v37, v86
	v_fmac_f32_e32 v97, v81, v36
	v_fmac_f32_e32 v96, v80, v36
	v_fmac_f32_e32 v95, v79, v36
	v_fmac_f32_e32 v94, v78, v36
	v_fmac_f32_e32 v93, v77, v36
	v_fmac_f32_e32 v92, v76, v36
	v_fmac_f32_e32 v91, v75, v36
	v_fmac_f32_e32 v90, v74, v36
	v_fmac_f32_e32 v89, v73, v36
	v_fmac_f32_e32 v88, v72, v36
	v_fmac_f32_e32 v64, v71, v36
	v_fmac_f32_e32 v52, v70, v36
	v_fmac_f32_e32 v51, v69, v36
	v_fmac_f32_e32 v49, v68, v36
	v_fmac_f32_e32 v48, v67, v36
	v_fmac_f32_e32 v47, v66, v36
	v_fmac_f32_e32 v46, v63, v36
	v_fmac_f32_e32 v45, v62, v36
	v_fmac_f32_e32 v44, v61, v36
	v_fmac_f32_e32 v43, v60, v36
	v_fmac_f32_e32 v42, v59, v36
	v_fmac_f32_e32 v41, v58, v36
	v_fmac_f32_e32 v40, v57, v36
	v_fmac_f32_e32 v39, v56, v36
	v_fmac_f32_e32 v38, v55, v36
	v_fmac_f32_e32 v37, v54, v36
	v_fma_f32 v36, v53, v36, v86
	v_fmac_f32_e32 v97, v82, v33
	v_fmac_f32_e32 v96, v81, v33
	v_fmac_f32_e32 v95, v80, v33
	v_fmac_f32_e32 v94, v79, v33
	v_fmac_f32_e32 v93, v78, v33
	v_fmac_f32_e32 v92, v77, v33
	v_fmac_f32_e32 v91, v76, v33
	v_fmac_f32_e32 v90, v75, v33
	v_fmac_f32_e32 v89, v74, v33
	v_fmac_f32_e32 v88, v73, v33
	v_fmac_f32_e32 v64, v72, v33
	v_fmac_f32_e32 v52, v71, v33
	v_fmac_f32_e32 v51, v70, v33
	v_fmac_f32_e32 v49, v69, v33
	v_fmac_f32_e32 v48, v68, v33
	v_fmac_f32_e32 v47, v67, v33
	v_fmac_f32_e32 v46, v66, v33
	v_fmac_f32_e32 v45, v63, v33
	v_fmac_f32_e32 v44, v62, v33
	v_fmac_f32_e32 v43, v61, v33
	v_fmac_f32_e32 v42, v60, v33
	v_fmac_f32_e32 v41, v59, v33
	v_fmac_f32_e32 v40, v58, v33
	v_fmac_f32_e32 v39, v57, v33
	v_fmac_f32_e32 v38, v56, v33
	v_fmac_f32_e32 v37, v55, v33
	v_fmac_f32_e32 v36, v54, v33
	v_fma_f32 v33, v53, v33, v86
	v_fmac_f32_e32 v97, v83, v26
	v_fmac_f32_e32 v96, v82, v26
	v_fmac_f32_e32 v95, v81, v26
	v_fmac_f32_e32 v94, v80, v26
	v_fmac_f32_e32 v93, v79, v26
	v_fmac_f32_e32 v92, v78, v26
	v_fmac_f32_e32 v91, v77, v26
	v_fmac_f32_e32 v90, v76, v26
	v_fmac_f32_e32 v89, v75, v26
	v_fmac_f32_e32 v88, v74, v26
	v_fmac_f32_e32 v64, v73, v26
	v_fmac_f32_e32 v52, v72, v26
	v_fmac_f32_e32 v51, v71, v26
	v_fmac_f32_e32 v49, v70, v26
	v_fmac_f32_e32 v48, v69, v26
	v_fmac_f32_e32 v47, v68, v26
	v_fmac_f32_e32 v46, v67, v26
	v_fmac_f32_e32 v45, v66, v26
	v_fmac_f32_e32 v44, v63, v26
	v_fmac_f32_e32 v43, v62, v26
	v_fmac_f32_e32 v42, v61, v26
	v_fmac_f32_e32 v41, v60, v26
	v_fmac_f32_e32 v40, v59, v26
	v_fmac_f32_e32 v39, v58, v26
	v_fmac_f32_e32 v38, v57, v26
	v_fmac_f32_e32 v37, v56, v26
	v_fmac_f32_e32 v36, v55, v26
	v_fmac_f32_e32 v33, v54, v26
	v_fma_f32 v26, v53, v26, v86
	v_fmac_f32_e32 v97, v84, v17
	v_fmac_f32_e32 v96, v83, v17
	v_fmac_f32_e32 v95, v82, v17
	v_fmac_f32_e32 v94, v81, v17
	v_fmac_f32_e32 v93, v80, v17
	v_fmac_f32_e32 v92, v79, v17
	v_fmac_f32_e32 v91, v78, v17
	v_fmac_f32_e32 v90, v77, v17
	v_fmac_f32_e32 v89, v76, v17
	v_fmac_f32_e32 v88, v75, v17
	v_fmac_f32_e32 v64, v74, v17
	v_fmac_f32_e32 v52, v73, v17
	v_fmac_f32_e32 v51, v72, v17
	v_fmac_f32_e32 v49, v71, v17
	v_fmac_f32_e32 v48, v70, v17
	v_fmac_f32_e32 v47, v69, v17
	v_fmac_f32_e32 v46, v68, v17
	v_fmac_f32_e32 v45, v67, v17
	v_fmac_f32_e32 v44, v66, v17
	v_fmac_f32_e32 v43, v63, v17
	v_fmac_f32_e32 v42, v62, v17
	v_fmac_f32_e32 v41, v61, v17
	v_fmac_f32_e32 v40, v60, v17
	v_fmac_f32_e32 v39, v59, v17
	v_fmac_f32_e32 v38, v58, v17
	v_fmac_f32_e32 v37, v57, v17
	v_fmac_f32_e32 v36, v56, v17
	v_fmac_f32_e32 v33, v55, v17
	v_fmac_f32_e32 v26, v54, v17
	v_fma_f32 v17, v53, v17, v86
	s_waitcnt lgkmcnt(0)
	v_lshlrev_b32_e32 v0, 16, v0
	v_fmac_f32_e32 v97, v85, v8
	v_fmac_f32_e32 v96, v84, v8
	v_fmac_f32_e32 v95, v83, v8
	v_fmac_f32_e32 v94, v82, v8
	v_fmac_f32_e32 v93, v81, v8
	v_fmac_f32_e32 v92, v80, v8
	v_fmac_f32_e32 v91, v79, v8
	v_fmac_f32_e32 v90, v78, v8
	v_fmac_f32_e32 v89, v77, v8
	v_fmac_f32_e32 v88, v76, v8
	v_fmac_f32_e32 v64, v75, v8
	v_fmac_f32_e32 v52, v74, v8
	v_fmac_f32_e32 v51, v73, v8
	v_fmac_f32_e32 v49, v72, v8
	v_fmac_f32_e32 v48, v71, v8
	v_fmac_f32_e32 v47, v70, v8
	v_fmac_f32_e32 v46, v69, v8
	v_fmac_f32_e32 v45, v68, v8
	v_fmac_f32_e32 v44, v67, v8
	v_fmac_f32_e32 v43, v66, v8
	v_fmac_f32_e32 v42, v63, v8
	v_fmac_f32_e32 v41, v62, v8
	v_fmac_f32_e32 v40, v61, v8
	v_fmac_f32_e32 v39, v60, v8
	v_fmac_f32_e32 v38, v59, v8
	v_fmac_f32_e32 v37, v58, v8
	v_fmac_f32_e32 v36, v57, v8
	v_fmac_f32_e32 v33, v56, v8
	v_fmac_f32_e32 v26, v55, v8
	v_fmac_f32_e32 v17, v54, v8
	v_fma_f32 v8, v53, v8, v86
	v_fmac_f32_e32 v96, v85, v0
	v_fmac_f32_e32 v95, v84, v0
	v_fmac_f32_e32 v94, v83, v0
	v_fmac_f32_e32 v93, v82, v0
	v_fmac_f32_e32 v92, v81, v0
	v_fmac_f32_e32 v91, v80, v0
	v_fmac_f32_e32 v90, v79, v0
	v_fmac_f32_e32 v89, v78, v0
	v_fmac_f32_e32 v88, v77, v0
	v_fmac_f32_e32 v64, v76, v0
	v_fmac_f32_e32 v52, v75, v0
	v_fmac_f32_e32 v51, v74, v0
	v_fmac_f32_e32 v49, v73, v0
	v_fmac_f32_e32 v48, v72, v0
	v_fmac_f32_e32 v47, v71, v0
	v_fmac_f32_e32 v46, v70, v0
	v_fmac_f32_e32 v45, v69, v0
	v_fmac_f32_e32 v44, v68, v0
	v_fmac_f32_e32 v43, v67, v0
	v_fmac_f32_e32 v42, v66, v0
	v_fmac_f32_e32 v41, v63, v0
	v_fmac_f32_e32 v40, v62, v0
	v_fmac_f32_e32 v39, v61, v0
	v_fmac_f32_e32 v38, v60, v0
	v_fmac_f32_e32 v37, v59, v0
	v_fmac_f32_e32 v36, v58, v0
	v_fmac_f32_e32 v33, v57, v0
	v_fmac_f32_e32 v26, v56, v0
	v_fmac_f32_e32 v17, v55, v0
	v_fmac_f32_e32 v8, v54, v0
	v_fma_f32 v0, v53, v0, v86
	v_fmac_f32_e32 v0, v54, v1
	v_lshlrev_b32_e32 v3, 16, v3
	v_fmac_f32_e32 v0, v55, v2
	v_lshlrev_b32_e32 v4, 16, v4
	v_fmac_f32_e32 v0, v56, v3
	v_lshlrev_b32_e32 v5, 16, v5
	v_fmac_f32_e32 v8, v55, v1
	v_fmac_f32_e32 v0, v57, v4
	v_lshlrev_b32_e32 v6, 16, v6
	v_fmac_f32_e32 v17, v56, v1
	v_fmac_f32_e32 v8, v56, v2
	v_fmac_f32_e32 v0, v58, v5
	v_lshlrev_b32_e32 v7, 16, v7
	v_fmac_f32_e32 v26, v57, v1
	v_fmac_f32_e32 v17, v57, v2
	v_fmac_f32_e32 v8, v57, v3
	v_fmac_f32_e32 v0, v59, v6
	v_lshlrev_b32_e32 v9, 16, v9
	v_fmac_f32_e32 v36, v59, v1
	v_fmac_f32_e32 v33, v58, v1
	v_fmac_f32_e32 v26, v58, v2
	v_fmac_f32_e32 v17, v58, v3
	v_fmac_f32_e32 v8, v58, v4
	v_fmac_f32_e32 v0, v60, v7
	v_lshlrev_b32_e32 v10, 16, v10
	v_fmac_f32_e32 v37, v60, v1
	v_fmac_f32_e32 v36, v60, v2
	v_fmac_f32_e32 v33, v59, v2
	v_fmac_f32_e32 v26, v59, v3
	v_fmac_f32_e32 v17, v59, v4
	v_fmac_f32_e32 v8, v59, v5
	v_fmac_f32_e32 v0, v61, v9
	v_lshlrev_b32_e32 v11, 16, v11
	v_fmac_f32_e32 v37, v61, v2
	v_fmac_f32_e32 v36, v61, v3
	v_fmac_f32_e32 v33, v60, v3
	v_fmac_f32_e32 v26, v60, v4
	v_fmac_f32_e32 v17, v60, v5
	v_fmac_f32_e32 v8, v60, v6
	v_fmac_f32_e32 v0, v62, v10
	v_lshlrev_b32_e32 v12, 16, v12
	v_fmac_f32_e32 v38, v61, v1
	v_fmac_f32_e32 v37, v62, v3
	v_fmac_f32_e32 v36, v62, v4
	v_fmac_f32_e32 v33, v61, v4
	v_fmac_f32_e32 v26, v61, v5
	v_fmac_f32_e32 v17, v61, v6
	v_fmac_f32_e32 v8, v61, v7
	v_fmac_f32_e32 v0, v63, v11
	v_lshlrev_b32_e32 v13, 16, v13
	v_fmac_f32_e32 v42, v67, v1
	v_fmac_f32_e32 v39, v62, v1
	v_fmac_f32_e32 v38, v62, v2
	v_fmac_f32_e32 v37, v63, v4
	v_fmac_f32_e32 v36, v63, v5
	v_fmac_f32_e32 v33, v62, v5
	v_fmac_f32_e32 v26, v62, v6
	v_fmac_f32_e32 v17, v62, v7
	v_fmac_f32_e32 v8, v62, v9
	v_fmac_f32_e32 v0, v66, v12
	v_lshlrev_b32_e32 v14, 16, v14
	v_fmac_f32_e32 v43, v68, v1
	v_fmac_f32_e32 v42, v68, v2
	v_fmac_f32_e32 v40, v63, v1
	v_fmac_f32_e32 v39, v63, v2
	v_fmac_f32_e32 v38, v63, v3
	v_fmac_f32_e32 v37, v66, v5
	v_fmac_f32_e32 v36, v66, v6
	v_fmac_f32_e32 v33, v63, v6
	v_fmac_f32_e32 v26, v63, v7
	v_fmac_f32_e32 v17, v63, v9
	v_fmac_f32_e32 v8, v63, v10
	v_fmac_f32_e32 v0, v67, v13
	v_lshlrev_b32_e32 v15, 16, v15
	v_fmac_f32_e32 v43, v69, v2
	v_fmac_f32_e32 v42, v69, v3
	v_fmac_f32_e32 v41, v66, v1
	v_fmac_f32_e32 v40, v66, v2
	v_fmac_f32_e32 v39, v66, v3
	v_fmac_f32_e32 v38, v66, v4
	v_fmac_f32_e32 v37, v67, v6
	v_fmac_f32_e32 v36, v67, v7
	v_fmac_f32_e32 v33, v66, v7
	v_fmac_f32_e32 v26, v66, v9
	v_fmac_f32_e32 v17, v66, v10
	v_fmac_f32_e32 v8, v66, v11
	v_fmac_f32_e32 v0, v68, v14
	v_lshlrev_b32_e32 v16, 16, v16
	v_fmac_f32_e32 v43, v70, v3
	v_fmac_f32_e32 v42, v70, v4
	v_fmac_f32_e32 v41, v67, v2
	v_fmac_f32_e32 v40, v67, v3
	v_fmac_f32_e32 v39, v67, v4
	v_fmac_f32_e32 v38, v67, v5
	v_fmac_f32_e32 v37, v68, v7
	v_fmac_f32_e32 v36, v68, v9
	v_fmac_f32_e32 v33, v67, v9
	v_fmac_f32_e32 v26, v67, v10
	v_fmac_f32_e32 v17, v67, v11
	v_fmac_f32_e32 v8, v67, v12
	v_fmac_f32_e32 v0, v69, v15
	v_lshlrev_b32_e32 v18, 16, v18
	v_fmac_f32_e32 v43, v71, v4
	v_fmac_f32_e32 v42, v71, v5
	v_fmac_f32_e32 v41, v68, v3
	v_fmac_f32_e32 v40, v68, v4
	v_fmac_f32_e32 v39, v68, v5
	v_fmac_f32_e32 v38, v68, v6
	v_fmac_f32_e32 v37, v69, v9
	v_fmac_f32_e32 v36, v69, v10
	v_fmac_f32_e32 v33, v68, v10
	v_fmac_f32_e32 v26, v68, v11
	v_fmac_f32_e32 v17, v68, v12
	v_fmac_f32_e32 v8, v68, v13
	v_fmac_f32_e32 v0, v70, v16
	v_lshlrev_b32_e32 v19, 16, v19
	v_fmac_f32_e32 v46, v71, v1
	v_fmac_f32_e32 v44, v69, v1
	v_fmac_f32_e32 v43, v72, v5
	v_fmac_f32_e32 v42, v72, v6
	v_fmac_f32_e32 v41, v69, v4
	v_fmac_f32_e32 v40, v69, v5
	v_fmac_f32_e32 v39, v69, v6
	v_fmac_f32_e32 v38, v69, v7
	v_fmac_f32_e32 v37, v70, v10
	v_fmac_f32_e32 v36, v70, v11
	v_fmac_f32_e32 v33, v69, v11
	v_fmac_f32_e32 v26, v69, v12
	v_fmac_f32_e32 v17, v69, v13
	v_fmac_f32_e32 v8, v69, v14
	v_fmac_f32_e32 v0, v71, v18
	v_lshlrev_b32_e32 v20, 16, v20
	v_fmac_f32_e32 v47, v72, v1
	v_fmac_f32_e32 v46, v72, v2
	v_fmac_f32_e32 v45, v70, v1
	v_fmac_f32_e32 v44, v70, v2
	v_fmac_f32_e32 v43, v73, v6
	v_fmac_f32_e32 v42, v73, v7
	v_fmac_f32_e32 v41, v70, v5
	v_fmac_f32_e32 v40, v70, v6
	v_fmac_f32_e32 v39, v70, v7
	v_fmac_f32_e32 v38, v70, v9
	v_fmac_f32_e32 v37, v71, v11
	v_fmac_f32_e32 v36, v71, v12
	v_fmac_f32_e32 v33, v70, v12
	v_fmac_f32_e32 v26, v70, v13
	v_fmac_f32_e32 v17, v70, v14
	v_fmac_f32_e32 v8, v70, v15
	v_fmac_f32_e32 v0, v72, v19
	v_lshlrev_b32_e32 v21, 16, v21
	v_fmac_f32_e32 v48, v73, v1
	v_fmac_f32_e32 v47, v73, v2
	v_fmac_f32_e32 v46, v73, v3
	v_fmac_f32_e32 v45, v71, v2
	v_fmac_f32_e32 v44, v71, v3
	v_fmac_f32_e32 v43, v74, v7
	v_fmac_f32_e32 v42, v74, v9
	v_fmac_f32_e32 v41, v71, v6
	v_fmac_f32_e32 v40, v71, v7
	v_fmac_f32_e32 v39, v71, v9
	v_fmac_f32_e32 v38, v71, v10
	v_fmac_f32_e32 v37, v72, v12
	v_fmac_f32_e32 v36, v72, v13
	v_fmac_f32_e32 v33, v71, v13
	v_fmac_f32_e32 v26, v71, v14
	v_fmac_f32_e32 v17, v71, v15
	v_fmac_f32_e32 v8, v71, v16
	v_fmac_f32_e32 v0, v73, v20
	v_lshlrev_b32_e32 v22, 16, v22
	v_fmac_f32_e32 v49, v74, v1
	v_fmac_f32_e32 v48, v74, v2
	v_fmac_f32_e32 v47, v74, v3
	v_fmac_f32_e32 v46, v74, v4
	v_fmac_f32_e32 v45, v72, v3
	v_fmac_f32_e32 v44, v72, v4
	v_fmac_f32_e32 v43, v75, v9
	v_fmac_f32_e32 v42, v75, v10
	v_fmac_f32_e32 v41, v72, v7
	v_fmac_f32_e32 v40, v72, v9
	v_fmac_f32_e32 v39, v72, v10
	v_fmac_f32_e32 v38, v72, v11
	v_fmac_f32_e32 v37, v73, v13
	v_fmac_f32_e32 v36, v73, v14
	v_fmac_f32_e32 v33, v72, v14
	v_fmac_f32_e32 v26, v72, v15
	v_fmac_f32_e32 v17, v72, v16
	v_fmac_f32_e32 v8, v72, v18
	v_fmac_f32_e32 v0, v74, v21
	v_lshlrev_b32_e32 v23, 16, v23
	v_fmac_f32_e32 v51, v75, v1
	v_fmac_f32_e32 v49, v75, v2
	v_fmac_f32_e32 v48, v75, v3
	v_fmac_f32_e32 v47, v75, v4
	v_fmac_f32_e32 v46, v75, v5
	v_fmac_f32_e32 v45, v73, v4
	v_fmac_f32_e32 v44, v73, v5
	v_fmac_f32_e32 v43, v76, v10
	v_fmac_f32_e32 v42, v76, v11
	v_fmac_f32_e32 v41, v73, v9
	v_fmac_f32_e32 v40, v73, v10
	v_fmac_f32_e32 v39, v73, v11
	v_fmac_f32_e32 v38, v73, v12
	v_fmac_f32_e32 v37, v74, v14
	v_fmac_f32_e32 v36, v74, v15
	v_fmac_f32_e32 v33, v73, v15
	v_fmac_f32_e32 v26, v73, v16
	v_fmac_f32_e32 v17, v73, v18
	v_fmac_f32_e32 v8, v73, v19
	v_fmac_f32_e32 v0, v75, v22
	v_lshlrev_b32_e32 v24, 16, v24
	v_fmac_f32_e32 v52, v76, v1
	v_fmac_f32_e32 v51, v76, v2
	v_fmac_f32_e32 v49, v76, v3
	v_fmac_f32_e32 v48, v76, v4
	v_fmac_f32_e32 v47, v76, v5
	v_fmac_f32_e32 v46, v76, v6
	v_fmac_f32_e32 v45, v74, v5
	v_fmac_f32_e32 v44, v74, v6
	v_fmac_f32_e32 v43, v77, v11
	v_fmac_f32_e32 v42, v77, v12
	v_fmac_f32_e32 v41, v74, v10
	v_fmac_f32_e32 v40, v74, v11
	v_fmac_f32_e32 v39, v74, v12
	v_fmac_f32_e32 v38, v74, v13
	v_fmac_f32_e32 v37, v75, v15
	v_fmac_f32_e32 v36, v75, v16
	v_fmac_f32_e32 v33, v74, v16
	v_fmac_f32_e32 v26, v74, v18
	v_fmac_f32_e32 v17, v74, v19
	v_fmac_f32_e32 v8, v74, v20
	v_fmac_f32_e32 v0, v76, v23
	v_lshlrev_b32_e32 v25, 16, v25
	v_fmac_f32_e32 v64, v77, v1
	v_fmac_f32_e32 v52, v77, v2
	v_fmac_f32_e32 v51, v77, v3
	v_fmac_f32_e32 v49, v77, v4
	v_fmac_f32_e32 v48, v77, v5
	v_fmac_f32_e32 v47, v77, v6
	v_fmac_f32_e32 v46, v77, v7
	v_fmac_f32_e32 v45, v75, v6
	v_fmac_f32_e32 v44, v75, v7
	v_fmac_f32_e32 v43, v78, v12
	v_fmac_f32_e32 v42, v78, v13
	v_fmac_f32_e32 v41, v75, v11
	v_fmac_f32_e32 v40, v75, v12
	v_fmac_f32_e32 v39, v75, v13
	v_fmac_f32_e32 v38, v75, v14
	v_fmac_f32_e32 v37, v76, v16
	v_fmac_f32_e32 v36, v76, v18
	v_fmac_f32_e32 v33, v75, v18
	v_fmac_f32_e32 v26, v75, v19
	v_fmac_f32_e32 v17, v75, v20
	v_fmac_f32_e32 v8, v75, v21
	v_fmac_f32_e32 v0, v77, v24
	v_lshlrev_b32_e32 v27, 16, v27
	v_fmac_f32_e32 v88, v78, v1
	v_fmac_f32_e32 v64, v78, v2
	v_fmac_f32_e32 v52, v78, v3
	v_fmac_f32_e32 v51, v78, v4
	v_fmac_f32_e32 v49, v78, v5
	v_fmac_f32_e32 v48, v78, v6
	v_fmac_f32_e32 v47, v78, v7
	v_fmac_f32_e32 v46, v78, v9
	v_fmac_f32_e32 v45, v76, v7
	v_fmac_f32_e32 v44, v76, v9
	v_fmac_f32_e32 v43, v79, v13
	v_fmac_f32_e32 v42, v79, v14
	v_fmac_f32_e32 v41, v76, v12
	v_fmac_f32_e32 v40, v76, v13
	v_fmac_f32_e32 v39, v76, v14
	v_fmac_f32_e32 v38, v76, v15
	v_fmac_f32_e32 v37, v77, v18
	v_fmac_f32_e32 v36, v77, v19
	v_fmac_f32_e32 v33, v76, v19
	v_fmac_f32_e32 v26, v76, v20
	v_fmac_f32_e32 v17, v76, v21
	v_fmac_f32_e32 v8, v76, v22
	v_fmac_f32_e32 v0, v78, v25
	v_lshlrev_b32_e32 v28, 16, v28
	ds_read_u16 v34, v34 offset:31232
	v_fmac_f32_e32 v89, v79, v1
	v_fmac_f32_e32 v88, v79, v2
	v_fmac_f32_e32 v64, v79, v3
	v_fmac_f32_e32 v52, v79, v4
	v_fmac_f32_e32 v51, v79, v5
	v_fmac_f32_e32 v49, v79, v6
	v_fmac_f32_e32 v48, v79, v7
	v_fmac_f32_e32 v47, v79, v9
	v_fmac_f32_e32 v46, v79, v10
	v_fmac_f32_e32 v45, v77, v9
	v_fmac_f32_e32 v44, v77, v10
	v_fmac_f32_e32 v43, v80, v14
	v_fmac_f32_e32 v42, v80, v15
	v_fmac_f32_e32 v41, v77, v13
	v_fmac_f32_e32 v40, v77, v14
	v_fmac_f32_e32 v39, v77, v15
	v_fmac_f32_e32 v38, v77, v16
	v_fmac_f32_e32 v37, v78, v19
	v_fmac_f32_e32 v36, v78, v20
	v_fmac_f32_e32 v33, v77, v20
	v_fmac_f32_e32 v26, v77, v21
	v_fmac_f32_e32 v17, v77, v22
	v_fmac_f32_e32 v8, v77, v23
	v_fmac_f32_e32 v0, v79, v27
	v_lshlrev_b32_e32 v29, 16, v29
	v_fmac_f32_e32 v90, v80, v1
	v_fmac_f32_e32 v89, v80, v2
	v_fmac_f32_e32 v88, v80, v3
	v_fmac_f32_e32 v64, v80, v4
	v_fmac_f32_e32 v52, v80, v5
	v_fmac_f32_e32 v51, v80, v6
	v_fmac_f32_e32 v49, v80, v7
	v_fmac_f32_e32 v48, v80, v9
	v_fmac_f32_e32 v47, v80, v10
	v_fmac_f32_e32 v46, v80, v11
	v_fmac_f32_e32 v45, v78, v10
	v_fmac_f32_e32 v44, v78, v11
	v_fmac_f32_e32 v43, v81, v15
	v_fmac_f32_e32 v42, v81, v16
	v_fmac_f32_e32 v41, v78, v14
	v_fmac_f32_e32 v40, v78, v15
	v_fmac_f32_e32 v39, v78, v16
	v_fmac_f32_e32 v38, v78, v18
	v_fmac_f32_e32 v37, v79, v20
	v_fmac_f32_e32 v36, v79, v21
	v_fmac_f32_e32 v33, v78, v21
	v_fmac_f32_e32 v26, v78, v22
	v_fmac_f32_e32 v17, v78, v23
	v_fmac_f32_e32 v8, v78, v24
	v_fmac_f32_e32 v0, v80, v28
	v_lshlrev_b32_e32 v30, 16, v30
	v_fmac_f32_e32 v91, v81, v1
	v_fmac_f32_e32 v90, v81, v2
	v_fmac_f32_e32 v89, v81, v3
	v_fmac_f32_e32 v88, v81, v4
	v_fmac_f32_e32 v64, v81, v5
	v_fmac_f32_e32 v52, v81, v6
	v_fmac_f32_e32 v51, v81, v7
	v_fmac_f32_e32 v49, v81, v9
	v_fmac_f32_e32 v48, v81, v10
	v_fmac_f32_e32 v47, v81, v11
	v_fmac_f32_e32 v46, v81, v12
	v_fmac_f32_e32 v45, v79, v11
	v_fmac_f32_e32 v44, v79, v12
	v_fmac_f32_e32 v43, v82, v16
	v_fmac_f32_e32 v42, v82, v18
	v_fmac_f32_e32 v41, v79, v15
	v_fmac_f32_e32 v40, v79, v16
	v_fmac_f32_e32 v39, v79, v18
	v_fmac_f32_e32 v38, v79, v19
	v_fmac_f32_e32 v37, v80, v21
	v_fmac_f32_e32 v36, v80, v22
	v_fmac_f32_e32 v33, v79, v22
	v_fmac_f32_e32 v26, v79, v23
	v_fmac_f32_e32 v17, v79, v24
	v_fmac_f32_e32 v8, v79, v25
	v_fmac_f32_e32 v0, v81, v29
	v_lshlrev_b32_e32 v31, 16, v31
	v_fmac_f32_e32 v92, v82, v1
	v_fmac_f32_e32 v91, v82, v2
	v_fmac_f32_e32 v90, v82, v3
	v_fmac_f32_e32 v89, v82, v4
	v_fmac_f32_e32 v88, v82, v5
	v_fmac_f32_e32 v64, v82, v6
	v_fmac_f32_e32 v52, v82, v7
	v_fmac_f32_e32 v51, v82, v9
	v_fmac_f32_e32 v49, v82, v10
	v_fmac_f32_e32 v48, v82, v11
	v_fmac_f32_e32 v47, v82, v12
	v_fmac_f32_e32 v46, v82, v13
	v_fmac_f32_e32 v45, v80, v12
	v_fmac_f32_e32 v44, v80, v13
	v_fmac_f32_e32 v43, v83, v18
	v_fmac_f32_e32 v42, v83, v19
	v_fmac_f32_e32 v41, v80, v16
	v_fmac_f32_e32 v40, v80, v18
	v_fmac_f32_e32 v39, v80, v19
	v_fmac_f32_e32 v38, v80, v20
	v_fmac_f32_e32 v37, v81, v22
	v_fmac_f32_e32 v36, v81, v23
	v_fmac_f32_e32 v33, v80, v23
	v_fmac_f32_e32 v26, v80, v24
	v_fmac_f32_e32 v17, v80, v25
	v_fmac_f32_e32 v8, v80, v27
	v_fmac_f32_e32 v0, v82, v30
	v_lshlrev_b32_e32 v32, 16, v32
	v_add3_u32 v87, 0, v35, v87
	v_fmac_f32_e32 v93, v83, v1
	v_fmac_f32_e32 v92, v83, v2
	v_fmac_f32_e32 v91, v83, v3
	v_fmac_f32_e32 v90, v83, v4
	v_fmac_f32_e32 v89, v83, v5
	v_fmac_f32_e32 v88, v83, v6
	v_fmac_f32_e32 v64, v83, v7
	v_fmac_f32_e32 v52, v83, v9
	v_fmac_f32_e32 v51, v83, v10
	v_fmac_f32_e32 v49, v83, v11
	v_fmac_f32_e32 v48, v83, v12
	v_fmac_f32_e32 v47, v83, v13
	v_fmac_f32_e32 v46, v83, v14
	v_fmac_f32_e32 v45, v81, v13
	v_fmac_f32_e32 v44, v81, v14
	v_fmac_f32_e32 v43, v84, v19
	v_fmac_f32_e32 v42, v84, v20
	v_fmac_f32_e32 v41, v81, v18
	v_fmac_f32_e32 v40, v81, v19
	v_fmac_f32_e32 v39, v81, v20
	v_fmac_f32_e32 v38, v81, v21
	v_fmac_f32_e32 v37, v82, v23
	v_fmac_f32_e32 v36, v82, v24
	v_fmac_f32_e32 v33, v81, v24
	v_fmac_f32_e32 v26, v81, v25
	v_fmac_f32_e32 v17, v81, v27
	v_fmac_f32_e32 v8, v81, v28
	v_fmac_f32_e32 v0, v83, v31
	s_waitcnt lgkmcnt(0)
	v_lshlrev_b32_e32 v34, 16, v34
	v_add_u32_e32 v35, 0xbc00, v87
	v_fmac_f32_e32 v95, v85, v1
	v_fmac_f32_e32 v94, v84, v1
	v_fmac_f32_e32 v93, v84, v2
	v_fmac_f32_e32 v92, v84, v3
	v_fmac_f32_e32 v91, v84, v4
	v_fmac_f32_e32 v90, v84, v5
	v_fmac_f32_e32 v89, v84, v6
	v_fmac_f32_e32 v88, v84, v7
	v_fmac_f32_e32 v64, v84, v9
	v_fmac_f32_e32 v52, v84, v10
	v_fmac_f32_e32 v51, v84, v11
	v_fmac_f32_e32 v49, v84, v12
	v_fmac_f32_e32 v48, v84, v13
	v_fmac_f32_e32 v47, v84, v14
	v_fmac_f32_e32 v46, v84, v15
	v_fmac_f32_e32 v45, v82, v14
	v_fmac_f32_e32 v44, v82, v15
	v_fmac_f32_e32 v43, v85, v20
	v_fmac_f32_e32 v42, v85, v21
	v_fmac_f32_e32 v41, v82, v19
	v_fmac_f32_e32 v40, v82, v20
	v_fmac_f32_e32 v39, v82, v21
	v_fmac_f32_e32 v38, v82, v22
	v_fmac_f32_e32 v37, v83, v24
	v_fmac_f32_e32 v36, v83, v25
	v_fmac_f32_e32 v33, v82, v25
	v_fmac_f32_e32 v26, v82, v27
	v_fmac_f32_e32 v17, v82, v28
	v_fmac_f32_e32 v8, v82, v29
	v_fmac_f32_e32 v0, v84, v32
	v_lshlrev_b32_e32 v1, 5, v50
	v_fmac_f32_e32 v94, v85, v2
	v_fmac_f32_e32 v93, v85, v3
	v_fmac_f32_e32 v92, v85, v4
	v_fmac_f32_e32 v91, v85, v5
	v_fmac_f32_e32 v90, v85, v6
	v_fmac_f32_e32 v89, v85, v7
	v_fmac_f32_e32 v88, v85, v9
	v_fmac_f32_e32 v64, v85, v10
	v_fmac_f32_e32 v52, v85, v11
	v_fmac_f32_e32 v51, v85, v12
	v_fmac_f32_e32 v49, v85, v13
	v_fmac_f32_e32 v48, v85, v14
	v_fmac_f32_e32 v47, v85, v15
	v_fmac_f32_e32 v46, v85, v16
	v_fmac_f32_e32 v45, v83, v15
	v_fmac_f32_e32 v44, v83, v16
	ds_write2st64_b32 v35, v43, v42 offset0:76 offset1:80
	v_fmac_f32_e32 v41, v83, v20
	v_fmac_f32_e32 v40, v83, v21
	v_fmac_f32_e32 v39, v83, v22
	v_fmac_f32_e32 v38, v83, v23
	v_fmac_f32_e32 v37, v84, v25
	v_fmac_f32_e32 v36, v84, v27
	v_fmac_f32_e32 v33, v83, v27
	v_fmac_f32_e32 v26, v83, v28
	v_fmac_f32_e32 v17, v83, v29
	v_fmac_f32_e32 v8, v83, v30
	v_fmac_f32_e32 v0, v85, v34
	v_ashrrev_i32_e32 v42, 3, v50
	v_and_b32_e32 v43, 0xe0, v1
	ds_write2st64_b32 v87, v97, v96 offset0:188 offset1:192
	ds_write2st64_b32 v87, v95, v94 offset0:196 offset1:200
	ds_write2st64_b32 v87, v93, v92 offset0:204 offset1:208
	ds_write2st64_b32 v87, v91, v90 offset0:212 offset1:216
	ds_write2st64_b32 v87, v89, v88 offset0:220 offset1:224
	ds_write2st64_b32 v87, v64, v52 offset0:228 offset1:232
	ds_write2st64_b32 v87, v51, v49 offset0:236 offset1:240
	ds_write2st64_b32 v87, v48, v47 offset0:244 offset1:248
	ds_write_b32 v87, v46 offset:64512
	v_fmac_f32_e32 v45, v84, v16
	v_fmac_f32_e32 v44, v84, v18
	v_fmac_f32_e32 v41, v84, v21
	v_fmac_f32_e32 v40, v84, v22
	v_fmac_f32_e32 v39, v84, v23
	v_fmac_f32_e32 v38, v84, v24
	v_fmac_f32_e32 v37, v85, v27
	v_fmac_f32_e32 v36, v85, v28
	v_fmac_f32_e32 v33, v84, v28
	v_fmac_f32_e32 v26, v84, v29
	v_fmac_f32_e32 v17, v84, v30
	v_fmac_f32_e32 v8, v84, v31
	ds_write_b32 v35, v0 offset:31744
	v_lshlrev_b32_e32 v0, 10, v42
	v_lshlrev_b32_e32 v87, 2, v43
	global_load_dwordx4 v[104:107], v87, s[22:23] offset:16
	global_load_dwordx4 v[108:111], v87, s[22:23]
	global_load_dwordx4 v[118:121], v87, s[2:3] offset:16
	global_load_dwordx4 v[122:125], v87, s[2:3]
	global_load_dwordx4 v[126:129], v87, s[22:23] offset:48
	global_load_dwordx4 v[134:137], v87, s[22:23] offset:32
	global_load_dwordx4 v[138:141], v87, s[2:3] offset:48
	global_load_dwordx4 v[142:145], v87, s[2:3] offset:32
	global_load_dwordx4 v[146:149], v87, s[22:23] offset:80
	global_load_dwordx4 v[150:153], v87, s[22:23] offset:64
	global_load_dwordx4 v[154:157], v87, s[2:3] offset:80
	global_load_dwordx4 v[160:163], v87, s[2:3] offset:64
	global_load_dwordx4 v[168:171], v87, s[22:23] offset:112
	global_load_dwordx4 v[172:175], v87, s[22:23] offset:96
	global_load_dwordx4 v[176:179], v87, s[2:3] offset:112
	global_load_dwordx4 v[184:187], v87, s[2:3] offset:96
	v_fmac_f32_e32 v45, v85, v18
	v_fmac_f32_e32 v44, v85, v19
	v_fmac_f32_e32 v41, v85, v22
	v_fmac_f32_e32 v40, v85, v23
	v_fmac_f32_e32 v39, v85, v24
	v_fmac_f32_e32 v38, v85, v25
	ds_write2st64_b32 v35, v37, v36 offset0:100 offset1:104
	v_fmac_f32_e32 v33, v85, v29
	v_fmac_f32_e32 v26, v85, v30
	v_fmac_f32_e32 v17, v85, v31
	v_fmac_f32_e32 v8, v85, v32
	v_add3_u32 v37, 0, v0, v87
	ds_write2st64_b32 v35, v45, v44 offset0:68 offset1:72
	ds_write2st64_b32 v35, v41, v40 offset0:84 offset1:88
	ds_write2st64_b32 v35, v39, v38 offset0:92 offset1:96
	ds_write2st64_b32 v35, v33, v26 offset0:108 offset1:112
	ds_write2st64_b32 v35, v17, v8 offset0:116 offset1:120
	s_waitcnt lgkmcnt(0)
	s_barrier
	ds_read_b128 v[28:31], v37 offset:48128
	ds_read_b128 v[24:27], v37 offset:48144
	ds_read_b128 v[20:23], v37 offset:48160
	ds_read_b128 v[16:19], v37 offset:48176
	s_mov_b32 s0, 0x3b800000
	s_waitcnt lgkmcnt(3)
	v_pk_mul_f32 v[0:1], v[30:31], v[30:31]
	v_pk_mul_f32 v[2:3], v[28:29], v[28:29]
	v_mov_b32_e32 v6, v31
	v_pk_mov_b32 v[4:5], v[2:3], v[0:1] op_sel:[1,0]
	v_mov_b32_e32 v3, v1
	v_pk_add_f32 v[0:1], v[4:5], v[2:3]
	v_mov_b32_e32 v2, v28
	s_waitcnt lgkmcnt(2)
	v_mov_b32_e32 v3, v24
	v_mov_b32_e32 v4, v29
	v_mov_b32_e32 v5, v25
	v_pk_add_f32 v[2:3], v[2:3], v[4:5]
	v_mov_b32_e32 v4, v30
	v_mov_b32_e32 v5, v26
	v_mov_b32_e32 v7, v27
	v_pk_add_f32 v[4:5], v[4:5], v[6:7]
	v_pk_mul_f32 v[6:7], v[24:25], v[24:25]
	v_pk_add_f32 v[2:3], v[2:3], v[4:5]
	v_pk_mul_f32 v[4:5], v[26:27], v[26:27]
	v_add_f32_e32 v2, 0, v2
	v_pk_mov_b32 v[8:9], v[6:7], v[4:5] op_sel:[1,0]
	v_mov_b32_e32 v7, v5
	v_pk_add_f32 v[4:5], v[8:9], v[6:7]
	s_waitcnt lgkmcnt(1)
	v_mov_b32_e32 v6, v21
	v_mov_b32_e32 v7, v22
	v_mov_b32_e32 v8, v20
	v_mov_b32_e32 v9, v23
	v_pk_add_f32 v[6:7], v[6:7], v[8:9]
	v_add_f32_e32 v2, v2, v3
	v_pk_add_f32 v[6:7], v[6:7], v[6:7] op_sel:[0,1] op_sel_hi:[1,0]
	s_waitcnt lgkmcnt(0)
	v_mul_f32_e32 v3, v16, v16
	v_mul_f32_e32 v7, v17, v17
	v_pk_add_f32 v[0:1], v[0:1], v[0:1] op_sel:[0,1] op_sel_hi:[1,0]
	v_pk_add_f32 v[4:5], v[4:5], v[4:5] op_sel:[0,1] op_sel_hi:[1,0]
	v_mov_b32_e32 v1, v3
	v_mov_b32_e32 v5, v7
	v_pk_add_f32 v[0:1], v[0:1], v[4:5]
	v_mul_f32_e32 v4, v21, v21
	v_mul_f32_e32 v12, v23, v23
	v_mul_f32_e32 v9, v18, v18
	v_mul_f32_e32 v11, v19, v19
	v_pk_fma_f32 v[4:5], v[20:21], v[20:21], v[4:5] op_sel_hi:[1,1,0]
	v_pk_fma_f32 v[12:13], v[22:23], v[22:23], v[12:13] op_sel_hi:[1,1,0]
	v_mov_b32_e32 v5, v9
	v_mov_b32_e32 v13, v11
	v_pk_add_f32 v[4:5], v[4:5], v[12:13]
	ds_read_b128 v[12:15], v37 offset:48192
	v_add_f32_e32 v8, v16, v17
	v_add_f32_e32 v10, v18, v19
	v_pk_add_f32 v[0:1], v[0:1], v[4:5]
	v_lshlrev_b32_e32 v64, 1, v43
	s_waitcnt lgkmcnt(0)
	v_mov_b32_e32 v9, v14
	v_mov_b32_e32 v11, v15
	v_mov_b32_e32 v3, v12
	v_mov_b32_e32 v7, v13
	v_pk_add_f32 v[4:5], v[8:9], v[10:11]
	ds_read_b128 v[8:11], v37 offset:48208
	v_pk_add_f32 v[2:3], v[2:3], v[6:7]
	v_pk_add_f32 v[0:1], v[0:1], v[0:1] op_sel:[0,1] op_sel_hi:[1,0]
	v_pk_add_f32 v[2:3], v[2:3], v[4:5]
	v_pk_mul_f32 v[4:5], v[12:13], v[12:13]
	v_pk_add_f32 v[32:33], v[2:3], v[2:3] op_sel:[0,1] op_sel_hi:[1,0]
	v_pk_mul_f32 v[2:3], v[14:15], v[14:15]
	s_waitcnt lgkmcnt(0)
	v_mul_f32_e32 v40, v11, v11
	v_pk_mov_b32 v[6:7], v[4:5], v[2:3] op_sel:[1,0]
	v_mov_b32_e32 v5, v3
	v_pk_add_f32 v[2:3], v[6:7], v[4:5]
	v_mov_b32_e32 v4, v9
	v_mov_b32_e32 v5, v10
	v_mov_b32_e32 v6, v8
	v_mov_b32_e32 v7, v11
	v_pk_add_f32 v[4:5], v[4:5], v[6:7]
	v_pk_add_f32 v[2:3], v[2:3], v[2:3] op_sel:[0,1] op_sel_hi:[1,0]
	v_pk_add_f32 v[34:35], v[4:5], v[4:5] op_sel:[0,1] op_sel_hi:[1,0]
	ds_read_b128 v[4:7], v37 offset:48224
	v_pk_fma_f32 v[40:41], v[10:11], v[10:11], v[40:41] op_sel_hi:[1,1,0]
	s_add_i32 s67, s67, s10
	s_waitcnt lgkmcnt(0)
	v_mul_f32_e32 v33, v4, v4
	v_mul_f32_e32 v35, v5, v5
	v_mov_b32_e32 v1, v33
	v_mov_b32_e32 v3, v35
	v_pk_add_f32 v[0:1], v[0:1], v[2:3]
	v_mul_f32_e32 v2, v9, v9
	v_mul_f32_e32 v39, v6, v6
	v_mul_f32_e32 v44, v7, v7
	v_pk_fma_f32 v[2:3], v[8:9], v[8:9], v[2:3] op_sel_hi:[1,1,0]
	v_mov_b32_e32 v41, v44
	v_mov_b32_e32 v3, v39
	v_pk_add_f32 v[2:3], v[2:3], v[40:41]
	v_add_f32_e32 v36, v4, v5
	v_pk_add_f32 v[0:1], v[0:1], v[2:3]
	v_add_f32_e32 v38, v6, v7
	v_pk_add_f32 v[40:41], v[0:1], v[0:1] op_sel:[0,1] op_sel_hi:[1,0]
	ds_read_b128 v[0:3], v37 offset:48240
	s_waitcnt lgkmcnt(0)
	v_mov_b32_e32 v33, v0
	v_mov_b32_e32 v35, v1
	v_mov_b32_e32 v37, v2
	v_mov_b32_e32 v39, v3
	v_pk_add_f32 v[32:33], v[32:33], v[34:35]
	v_pk_add_f32 v[34:35], v[36:37], v[38:39]
	v_pk_mul_f32 v[36:37], v[0:1], v[0:1]
	v_pk_add_f32 v[32:33], v[32:33], v[34:35]
	v_pk_mul_f32 v[34:35], v[2:3], v[2:3]
	v_mov_b32_e32 v41, v32
	v_pk_mov_b32 v[38:39], v[36:37], v[34:35] op_sel:[1,0]
	v_mov_b32_e32 v37, v35
	v_pk_add_f32 v[34:35], v[38:39], v[36:37]
	s_nop 0
	v_pk_add_f32 v[34:35], v[34:35], v[34:35] op_sel:[0,1] op_sel_hi:[1,0]
	s_nop 0
	v_mov_b32_e32 v35, v33
	v_pk_add_f32 v[32:33], v[40:41], v[34:35]
	ds_swizzle_b32 v35, v33 offset:swizzle(SWAP,1)
	ds_swizzle_b32 v34, v32 offset:swizzle(SWAP,1)
	s_waitcnt lgkmcnt(0)
	v_pk_add_f32 v[32:33], v[32:33], v[34:35]
	ds_swizzle_b32 v35, v33 offset:swizzle(SWAP,2)
	ds_swizzle_b32 v34, v32 offset:swizzle(SWAP,2)
	s_waitcnt lgkmcnt(0)
	v_pk_add_f32 v[32:33], v[32:33], v[34:35]
	ds_swizzle_b32 v35, v33 offset:swizzle(SWAP,4)
	ds_swizzle_b32 v34, v32 offset:swizzle(SWAP,4)
	s_waitcnt lgkmcnt(0)
	v_pk_add_f32 v[32:33], v[32:33], v[34:35]
	s_nop 0
	v_pk_mul_f32 v[50:51], v[32:33], s[0:1] op_sel_hi:[1,0]
	s_mov_b32 s0, 0x800000
	v_fma_f32 v32, -v51, v51, v50
	v_max_f32_e32 v32, 0, v32
	v_add_f32_e32 v32, 0x3727c5ac, v32
	v_cmp_gt_f32_e32 vcc, s0, v32
	v_mul_f32_e32 v33, 0x4b800000, v32
	v_pk_add_f32 v[28:29], v[28:29], v[50:51] op_sel:[0,1] neg_lo:[0,1] neg_hi:[0,1]
	v_cndmask_b32_e32 v32, v32, v33, vcc
	v_rsq_f32_e32 v32, v32
	v_pk_add_f32 v[24:25], v[24:25], v[50:51] op_sel:[0,1] neg_lo:[0,1] neg_hi:[0,1]
	v_pk_add_f32 v[20:21], v[20:21], v[50:51] op_sel:[0,1] neg_lo:[0,1] neg_hi:[0,1]
	v_pk_add_f32 v[16:17], v[16:17], v[50:51] op_sel:[0,1] neg_lo:[0,1] neg_hi:[0,1]
	v_mul_f32_e32 v33, 0x45800000, v32
	v_cndmask_b32_e32 v52, v32, v33, vcc
	v_add3_u32 v32, s34, v42, 15
	v_ashrrev_i32_e32 v33, 31, v32
	v_lshlrev_b64 v[32:33], 11, v[32:33]
	v_lshl_add_u64 v[32:33], s[8:9], 0, v[32:33]
	v_lshl_add_u64 v[48:49], v[32:33], 0, v[64:65]
	v_pk_mul_f32 v[28:29], v[28:29], v[52:53] op_sel_hi:[1,0]
	v_pk_mul_f32 v[24:25], v[24:25], v[52:53] op_sel_hi:[1,0]
	v_pk_mul_f32 v[20:21], v[20:21], v[52:53] op_sel_hi:[1,0]
	v_pk_mul_f32 v[16:17], v[16:17], v[52:53] op_sel_hi:[1,0]
	v_pk_add_f32 v[12:13], v[12:13], v[50:51] op_sel:[0,1] neg_lo:[0,1] neg_hi:[0,1]
	v_pk_add_f32 v[8:9], v[8:9], v[50:51] op_sel:[0,1] neg_lo:[0,1] neg_hi:[0,1]
	v_pk_mul_f32 v[12:13], v[12:13], v[52:53] op_sel_hi:[1,0]
	v_pk_mul_f32 v[8:9], v[8:9], v[52:53] op_sel_hi:[1,0]
	v_pk_add_f32 v[4:5], v[4:5], v[50:51] op_sel:[0,1] neg_lo:[0,1] neg_hi:[0,1]
	v_pk_add_f32 v[0:1], v[0:1], v[50:51] op_sel:[0,1] neg_lo:[0,1] neg_hi:[0,1]
	v_pk_mul_f32 v[4:5], v[4:5], v[52:53] op_sel_hi:[1,0]
	v_pk_mul_f32 v[0:1], v[0:1], v[52:53] op_sel_hi:[1,0]
	s_add_i32 s34, s34, s13
	s_cmpk_lt_i32 s67, 0xc0
	s_waitcnt vmcnt(0)
	v_pk_fma_f32 v[24:25], v[104:105], v[24:25], v[118:119]
	v_pk_fma_f32 v[28:29], v[108:109], v[28:29], v[122:123]
	s_nop 0
	v_mul_f32_e32 v40, 0xbfb8aa3b, v28
	v_mul_f32_e32 v41, 0xbfb8aa3b, v29
	v_exp_f32_e32 v40, v40
	v_exp_f32_e32 v41, v41
	s_nop 0
	v_pk_add_f32 v[40:41], v[40:41], 1.0 op_sel_hi:[1,0]
	s_nop 0
	v_div_scale_f32 v44, s[0:1], v41, v41, v29
	v_rcp_f32_e32 v45, v44
	s_nop 0
	v_fma_f32 v64, -v44, v45, 1.0
	v_fmac_f32_e32 v45, v64, v45
	v_div_scale_f32 v64, vcc, v29, v41, v29
	v_mul_f32_e32 v88, v64, v45
	v_fma_f32 v89, -v44, v88, v64
	v_fmac_f32_e32 v88, v89, v45
	v_fma_f32 v44, -v44, v88, v64
	v_div_fmas_f32 v44, v44, v45, v88
	v_div_fixup_f32 v41, v44, v41, v29
	v_div_scale_f32 v29, s[0:1], v40, v40, v28
	v_rcp_f32_e32 v44, v29
	s_nop 0
	v_fma_f32 v45, -v29, v44, 1.0
	v_fmac_f32_e32 v44, v45, v44
	v_div_scale_f32 v45, vcc, v28, v40, v28
	v_mul_f32_e32 v64, v45, v44
	v_fma_f32 v88, -v29, v64, v45
	v_fmac_f32_e32 v64, v88, v44
	v_fma_f32 v29, -v29, v64, v45
	v_div_fmas_f32 v29, v29, v44, v64
	v_div_fixup_f32 v40, v29, v40, v28
	v_pk_add_f32 v[28:29], v[30:31], v[50:51] op_sel:[0,1] neg_lo:[0,1] neg_hi:[0,1]
	s_nop 0
	v_pk_mul_f32 v[28:29], v[28:29], v[52:53] op_sel_hi:[1,0]
	s_nop 0
	v_pk_fma_f32 v[28:29], v[110:111], v[28:29], v[124:125]
	s_nop 0
	v_mul_f32_e32 v30, 0xbfb8aa3b, v28
	v_mul_f32_e32 v31, 0xbfb8aa3b, v29
	v_exp_f32_e32 v30, v30
	v_exp_f32_e32 v31, v31
	s_nop 0
	v_pk_add_f32 v[30:31], v[30:31], 1.0 op_sel_hi:[1,0]
	s_nop 0
	v_div_scale_f32 v42, s[0:1], v31, v31, v29
	v_rcp_f32_e32 v43, v42
	s_nop 0
	v_fma_f32 v44, -v42, v43, 1.0
	v_fmac_f32_e32 v43, v44, v43
	v_div_scale_f32 v44, vcc, v29, v31, v29
	v_mul_f32_e32 v45, v44, v43
	v_fma_f32 v46, -v42, v45, v44
	v_fmac_f32_e32 v45, v46, v43
	v_fma_f32 v42, -v42, v45, v44
	v_div_fmas_f32 v42, v42, v43, v45
	v_div_fixup_f32 v31, v42, v31, v29
	v_div_scale_f32 v29, s[0:1], v30, v30, v28
	v_rcp_f32_e32 v42, v29
	s_nop 0
	v_fma_f32 v43, -v29, v42, 1.0
	v_fmac_f32_e32 v42, v43, v42
	v_div_scale_f32 v43, vcc, v28, v30, v28
	v_mul_f32_e32 v44, v43, v42
	v_fma_f32 v45, -v29, v44, v43
	v_fmac_f32_e32 v44, v45, v42
	v_fma_f32 v29, -v29, v44, v43
	v_div_fmas_f32 v29, v29, v42, v44
	v_div_fixup_f32 v30, v29, v30, v28
	v_mul_f32_e32 v28, 0xbfb8aa3b, v24
	v_mul_f32_e32 v29, 0xbfb8aa3b, v25
	v_exp_f32_e32 v28, v28
	v_exp_f32_e32 v29, v29
	s_nop 0
	v_pk_add_f32 v[28:29], v[28:29], 1.0 op_sel_hi:[1,0]
	s_nop 0
	v_div_scale_f32 v32, s[0:1], v29, v29, v25
	v_rcp_f32_e32 v33, v32
	s_nop 0
	v_fma_f32 v36, -v32, v33, 1.0
	v_fmac_f32_e32 v33, v36, v33
	v_div_scale_f32 v36, vcc, v25, v29, v25
	v_mul_f32_e32 v37, v36, v33
	v_fma_f32 v42, -v32, v37, v36
	v_fmac_f32_e32 v37, v42, v33
	v_fma_f32 v32, -v32, v37, v36
	v_div_fmas_f32 v32, v32, v33, v37
	v_div_fixup_f32 v29, v32, v29, v25
	v_div_scale_f32 v25, s[0:1], v28, v28, v24
	v_rcp_f32_e32 v32, v25
	s_nop 0
	v_fma_f32 v33, -v25, v32, 1.0
	v_fmac_f32_e32 v32, v33, v32
	v_div_scale_f32 v33, vcc, v24, v28, v24
	v_mul_f32_e32 v36, v33, v32
	v_fma_f32 v37, -v25, v36, v33
	v_fmac_f32_e32 v36, v37, v32
	v_fma_f32 v25, -v25, v36, v33
	v_div_fmas_f32 v25, v25, v32, v36
	v_div_fixup_f32 v28, v25, v28, v24
	v_pk_add_f32 v[24:25], v[26:27], v[50:51] op_sel:[0,1] neg_lo:[0,1] neg_hi:[0,1]
	s_nop 0
	v_pk_mul_f32 v[24:25], v[24:25], v[52:53] op_sel_hi:[1,0]
	s_nop 0
	v_pk_fma_f32 v[24:25], v[24:25], v[106:107], v[120:121]
	s_nop 0
	v_mul_f32_e32 v26, 0xbfb8aa3b, v24
	v_mul_f32_e32 v27, 0xbfb8aa3b, v25
	v_exp_f32_e32 v26, v26
	v_exp_f32_e32 v27, v27
	s_nop 0
	v_pk_add_f32 v[26:27], v[26:27], 1.0 op_sel_hi:[1,0]
	s_nop 0
	v_div_scale_f32 v32, s[0:1], v27, v27, v25
	v_rcp_f32_e32 v33, v32
	s_nop 0
	v_fma_f32 v34, -v32, v33, 1.0
	v_fmac_f32_e32 v33, v34, v33
	v_div_scale_f32 v34, vcc, v25, v27, v25
	v_mul_f32_e32 v35, v34, v33
	v_fma_f32 v36, -v32, v35, v34
	v_fmac_f32_e32 v35, v36, v33
	v_fma_f32 v32, -v32, v35, v34
	v_div_fmas_f32 v32, v32, v33, v35
	v_div_fixup_f32 v27, v32, v27, v25
	v_div_scale_f32 v25, s[0:1], v26, v26, v24
	v_rcp_f32_e32 v32, v25
	s_nop 0
	v_fma_f32 v33, -v25, v32, 1.0
	v_fmac_f32_e32 v32, v33, v32
	v_div_scale_f32 v33, vcc, v24, v26, v24
	v_mul_f32_e32 v34, v33, v32
	v_fma_f32 v35, -v25, v34, v33
	v_fmac_f32_e32 v34, v35, v32
	v_fma_f32 v25, -v25, v34, v33
	v_div_fmas_f32 v25, v25, v32, v34
	v_div_fixup_f32 v32, v25, v26, v24
	v_cvt_pk_bf16_f32 v24, v40, v41
	v_cvt_pk_bf16_f32 v25, v30, v31
	v_cvt_pk_bf16_f32 v26, v28, v29
	v_cvt_pk_bf16_f32 v27, v32, v27
	global_store_dwordx4 v[48:49], v[24:27], off
	s_nop 0
	v_pk_fma_f32 v[16:17], v[16:17], v[126:127], v[138:139]
	v_pk_fma_f32 v[20:21], v[20:21], v[134:135], v[142:143]
	s_nop 0
	v_mul_f32_e32 v32, 0xbfb8aa3b, v20
	v_mul_f32_e32 v33, 0xbfb8aa3b, v21
	v_exp_f32_e32 v32, v32
	v_exp_f32_e32 v33, v33
	s_nop 0
	v_pk_add_f32 v[32:33], v[32:33], 1.0 op_sel_hi:[1,0]
	s_nop 0
	v_div_scale_f32 v36, s[0:1], v33, v33, v21
	v_rcp_f32_e32 v37, v36
	s_nop 0
	v_fma_f32 v40, -v36, v37, 1.0
	v_fmac_f32_e32 v37, v40, v37
	v_div_scale_f32 v40, vcc, v21, v33, v21
	v_mul_f32_e32 v41, v40, v37
	v_fma_f32 v42, -v36, v41, v40
	v_fmac_f32_e32 v41, v42, v37
	v_fma_f32 v36, -v36, v41, v40
	v_div_fmas_f32 v36, v36, v37, v41
	v_div_fixup_f32 v33, v36, v33, v21
	v_div_scale_f32 v21, s[0:1], v32, v32, v20
	v_rcp_f32_e32 v36, v21
	s_nop 0
	v_fma_f32 v37, -v21, v36, 1.0
	v_fmac_f32_e32 v36, v37, v36
	v_div_scale_f32 v37, vcc, v20, v32, v20
	v_mul_f32_e32 v40, v37, v36
	v_fma_f32 v41, -v21, v40, v37
	v_fmac_f32_e32 v40, v41, v36
	v_fma_f32 v21, -v21, v40, v37
	v_div_fmas_f32 v21, v21, v36, v40
	v_div_fixup_f32 v32, v21, v32, v20
	v_pk_add_f32 v[20:21], v[22:23], v[50:51] op_sel:[0,1] neg_lo:[0,1] neg_hi:[0,1]
	s_nop 0
	v_pk_mul_f32 v[20:21], v[20:21], v[52:53] op_sel_hi:[1,0]
	s_nop 0
	v_pk_fma_f32 v[20:21], v[20:21], v[136:137], v[144:145]
	s_nop 0
	v_mul_f32_e32 v22, 0xbfb8aa3b, v20
	v_mul_f32_e32 v23, 0xbfb8aa3b, v21
	v_exp_f32_e32 v22, v22
	v_exp_f32_e32 v23, v23
	s_nop 0
	v_pk_add_f32 v[22:23], v[22:23], 1.0 op_sel_hi:[1,0]
	s_nop 0
	v_div_scale_f32 v34, s[0:1], v23, v23, v21
	v_rcp_f32_e32 v35, v34
	s_nop 0
	v_fma_f32 v36, -v34, v35, 1.0
	v_fmac_f32_e32 v35, v36, v35
	v_div_scale_f32 v36, vcc, v21, v23, v21
	v_mul_f32_e32 v37, v36, v35
	v_fma_f32 v38, -v34, v37, v36
	v_fmac_f32_e32 v37, v38, v35
	v_fma_f32 v34, -v34, v37, v36
	v_div_fmas_f32 v34, v34, v35, v37
	v_div_fixup_f32 v23, v34, v23, v21
	v_div_scale_f32 v21, s[0:1], v22, v22, v20
	v_rcp_f32_e32 v34, v21
	s_nop 0
	v_fma_f32 v35, -v21, v34, 1.0
	v_fmac_f32_e32 v34, v35, v34
	v_div_scale_f32 v35, vcc, v20, v22, v20
	v_mul_f32_e32 v36, v35, v34
	v_fma_f32 v37, -v21, v36, v35
	v_fmac_f32_e32 v36, v37, v34
	v_fma_f32 v21, -v21, v36, v35
	v_div_fmas_f32 v21, v21, v34, v36
	v_div_fixup_f32 v22, v21, v22, v20
	v_mul_f32_e32 v20, 0xbfb8aa3b, v16
	v_mul_f32_e32 v21, 0xbfb8aa3b, v17
	v_exp_f32_e32 v20, v20
	v_exp_f32_e32 v21, v21
	s_nop 0
	v_pk_add_f32 v[20:21], v[20:21], 1.0 op_sel_hi:[1,0]
	s_nop 0
	v_div_scale_f32 v24, s[0:1], v21, v21, v17
	v_rcp_f32_e32 v25, v24
	s_nop 0
	v_fma_f32 v28, -v24, v25, 1.0
	v_fmac_f32_e32 v25, v28, v25
	v_div_scale_f32 v28, vcc, v17, v21, v17
	v_mul_f32_e32 v29, v28, v25
	v_fma_f32 v34, -v24, v29, v28
	v_fmac_f32_e32 v29, v34, v25
	v_fma_f32 v24, -v24, v29, v28
	v_div_fmas_f32 v24, v24, v25, v29
	v_div_fixup_f32 v21, v24, v21, v17
	v_div_scale_f32 v17, s[0:1], v20, v20, v16
	v_rcp_f32_e32 v24, v17
	s_nop 0
	v_fma_f32 v25, -v17, v24, 1.0
	v_fmac_f32_e32 v24, v25, v24
	v_div_scale_f32 v25, vcc, v16, v20, v16
	v_mul_f32_e32 v28, v25, v24
	v_fma_f32 v29, -v17, v28, v25
	v_fmac_f32_e32 v28, v29, v24
	v_fma_f32 v17, -v17, v28, v25
	v_div_fmas_f32 v17, v17, v24, v28
	v_div_fixup_f32 v20, v17, v20, v16
	v_pk_add_f32 v[16:17], v[18:19], v[50:51] op_sel:[0,1] neg_lo:[0,1] neg_hi:[0,1]
	s_nop 0
	v_pk_mul_f32 v[16:17], v[16:17], v[52:53] op_sel_hi:[1,0]
	s_nop 0
	v_pk_fma_f32 v[16:17], v[16:17], v[128:129], v[140:141]
	s_nop 0
	v_mul_f32_e32 v18, 0xbfb8aa3b, v16
	v_mul_f32_e32 v19, 0xbfb8aa3b, v17
	v_exp_f32_e32 v18, v18
	v_exp_f32_e32 v19, v19
	s_nop 0
	v_pk_add_f32 v[18:19], v[18:19], 1.0 op_sel_hi:[1,0]
	s_nop 0
	v_div_scale_f32 v24, s[0:1], v19, v19, v17
	v_rcp_f32_e32 v25, v24
	s_nop 0
	v_fma_f32 v26, -v24, v25, 1.0
	v_fmac_f32_e32 v25, v26, v25
	v_div_scale_f32 v26, vcc, v17, v19, v17
	v_mul_f32_e32 v27, v26, v25
	v_fma_f32 v28, -v24, v27, v26
	v_fmac_f32_e32 v27, v28, v25
	v_fma_f32 v24, -v24, v27, v26
	v_div_fmas_f32 v24, v24, v25, v27
	v_div_fixup_f32 v19, v24, v19, v17
	v_div_scale_f32 v17, s[0:1], v18, v18, v16
	v_rcp_f32_e32 v24, v17
	s_nop 0
	v_fma_f32 v25, -v17, v24, 1.0
	v_fmac_f32_e32 v24, v25, v24
	v_div_scale_f32 v25, vcc, v16, v18, v16
	v_mul_f32_e32 v26, v25, v24
	v_fma_f32 v27, -v17, v26, v25
	v_fmac_f32_e32 v26, v27, v24
	v_fma_f32 v17, -v17, v26, v25
	v_div_fmas_f32 v17, v17, v24, v26
	v_div_fixup_f32 v24, v17, v18, v16
	v_cvt_pk_bf16_f32 v16, v32, v33
	v_cvt_pk_bf16_f32 v17, v22, v23
	v_cvt_pk_bf16_f32 v18, v20, v21
	v_cvt_pk_bf16_f32 v19, v24, v19
	global_store_dwordx4 v[48:49], v[16:19], off offset:16
	s_nop 0
	v_pk_fma_f32 v[8:9], v[8:9], v[146:147], v[154:155]
	v_pk_fma_f32 v[12:13], v[12:13], v[150:151], v[160:161]
	s_nop 0
	v_mul_f32_e32 v24, 0xbfb8aa3b, v12
	v_mul_f32_e32 v25, 0xbfb8aa3b, v13
	v_exp_f32_e32 v24, v24
	v_exp_f32_e32 v25, v25
	s_nop 0
	v_pk_add_f32 v[24:25], v[24:25], 1.0 op_sel_hi:[1,0]
	s_nop 0
	v_div_scale_f32 v28, s[0:1], v25, v25, v13
	v_rcp_f32_e32 v29, v28
	s_nop 0
	v_fma_f32 v32, -v28, v29, 1.0
	v_fmac_f32_e32 v29, v32, v29
	v_div_scale_f32 v32, vcc, v13, v25, v13
	v_mul_f32_e32 v33, v32, v29
	v_fma_f32 v34, -v28, v33, v32
	v_fmac_f32_e32 v33, v34, v29
	v_fma_f32 v28, -v28, v33, v32
	v_div_fmas_f32 v28, v28, v29, v33
	v_div_fixup_f32 v25, v28, v25, v13
	v_div_scale_f32 v13, s[0:1], v24, v24, v12
	v_rcp_f32_e32 v28, v13
	s_nop 0
	v_fma_f32 v29, -v13, v28, 1.0
	v_fmac_f32_e32 v28, v29, v28
	v_div_scale_f32 v29, vcc, v12, v24, v12
	v_mul_f32_e32 v32, v29, v28
	v_fma_f32 v33, -v13, v32, v29
	v_fmac_f32_e32 v32, v33, v28
	v_fma_f32 v13, -v13, v32, v29
	v_div_fmas_f32 v13, v13, v28, v32
	v_div_fixup_f32 v24, v13, v24, v12
	v_pk_add_f32 v[12:13], v[14:15], v[50:51] op_sel:[0,1] neg_lo:[0,1] neg_hi:[0,1]
	s_nop 0
	v_pk_mul_f32 v[12:13], v[12:13], v[52:53] op_sel_hi:[1,0]
	s_nop 0
	v_pk_fma_f32 v[12:13], v[12:13], v[152:153], v[162:163]
	s_nop 0
	v_mul_f32_e32 v14, 0xbfb8aa3b, v12
	v_mul_f32_e32 v15, 0xbfb8aa3b, v13
	v_exp_f32_e32 v14, v14
	v_exp_f32_e32 v15, v15
	s_nop 0
	v_pk_add_f32 v[14:15], v[14:15], 1.0 op_sel_hi:[1,0]
	s_nop 0
	v_div_scale_f32 v26, s[0:1], v15, v15, v13
	v_rcp_f32_e32 v27, v26
	s_nop 0
	v_fma_f32 v28, -v26, v27, 1.0
	v_fmac_f32_e32 v27, v28, v27
	v_div_scale_f32 v28, vcc, v13, v15, v13
	v_mul_f32_e32 v29, v28, v27
	v_fma_f32 v30, -v26, v29, v28
	v_fmac_f32_e32 v29, v30, v27
	v_fma_f32 v26, -v26, v29, v28
	v_div_fmas_f32 v26, v26, v27, v29
	v_div_fixup_f32 v15, v26, v15, v13
	v_div_scale_f32 v13, s[0:1], v14, v14, v12
	v_rcp_f32_e32 v26, v13
	s_nop 0
	v_fma_f32 v27, -v13, v26, 1.0
	v_fmac_f32_e32 v26, v27, v26
	v_div_scale_f32 v27, vcc, v12, v14, v12
	v_mul_f32_e32 v28, v27, v26
	v_fma_f32 v29, -v13, v28, v27
	v_fmac_f32_e32 v28, v29, v26
	v_fma_f32 v13, -v13, v28, v27
	v_div_fmas_f32 v13, v13, v26, v28
	v_div_fixup_f32 v14, v13, v14, v12
	v_mul_f32_e32 v12, 0xbfb8aa3b, v8
	v_mul_f32_e32 v13, 0xbfb8aa3b, v9
	v_exp_f32_e32 v12, v12
	v_exp_f32_e32 v13, v13
	s_nop 0
	v_pk_add_f32 v[12:13], v[12:13], 1.0 op_sel_hi:[1,0]
	s_nop 0
	v_div_scale_f32 v16, s[0:1], v13, v13, v9
	v_rcp_f32_e32 v17, v16
	s_nop 0
	v_fma_f32 v20, -v16, v17, 1.0
	v_fmac_f32_e32 v17, v20, v17
	v_div_scale_f32 v20, vcc, v9, v13, v9
	v_mul_f32_e32 v21, v20, v17
	v_fma_f32 v26, -v16, v21, v20
	v_fmac_f32_e32 v21, v26, v17
	v_fma_f32 v16, -v16, v21, v20
	v_div_fmas_f32 v16, v16, v17, v21
	v_div_fixup_f32 v13, v16, v13, v9
	v_div_scale_f32 v9, s[0:1], v12, v12, v8
	v_rcp_f32_e32 v16, v9
	s_nop 0
	v_fma_f32 v17, -v9, v16, 1.0
	v_fmac_f32_e32 v16, v17, v16
	v_div_scale_f32 v17, vcc, v8, v12, v8
	v_mul_f32_e32 v20, v17, v16
	v_fma_f32 v21, -v9, v20, v17
	v_fmac_f32_e32 v20, v21, v16
	v_fma_f32 v9, -v9, v20, v17
	v_div_fmas_f32 v9, v9, v16, v20
	v_div_fixup_f32 v12, v9, v12, v8
	v_pk_add_f32 v[8:9], v[10:11], v[50:51] op_sel:[0,1] neg_lo:[0,1] neg_hi:[0,1]
	s_nop 0
	v_pk_mul_f32 v[8:9], v[8:9], v[52:53] op_sel_hi:[1,0]
	s_nop 0
	v_pk_fma_f32 v[8:9], v[8:9], v[148:149], v[156:157]
	s_nop 0
	v_mul_f32_e32 v10, 0xbfb8aa3b, v8
	v_mul_f32_e32 v11, 0xbfb8aa3b, v9
	v_exp_f32_e32 v10, v10
	v_exp_f32_e32 v11, v11
	s_nop 0
	v_pk_add_f32 v[10:11], v[10:11], 1.0 op_sel_hi:[1,0]
	s_nop 0
	v_div_scale_f32 v16, s[0:1], v11, v11, v9
	v_rcp_f32_e32 v17, v16
	s_nop 0
	v_fma_f32 v18, -v16, v17, 1.0
	v_fmac_f32_e32 v17, v18, v17
	v_div_scale_f32 v18, vcc, v9, v11, v9
	v_mul_f32_e32 v19, v18, v17
	v_fma_f32 v20, -v16, v19, v18
	v_fmac_f32_e32 v19, v20, v17
	v_fma_f32 v16, -v16, v19, v18
	v_div_fmas_f32 v16, v16, v17, v19
	v_div_fixup_f32 v11, v16, v11, v9
	v_div_scale_f32 v9, s[0:1], v10, v10, v8
	v_rcp_f32_e32 v16, v9
	s_nop 0
	v_fma_f32 v17, -v9, v16, 1.0
	v_fmac_f32_e32 v16, v17, v16
	v_div_scale_f32 v17, vcc, v8, v10, v8
	v_mul_f32_e32 v18, v17, v16
	v_fma_f32 v19, -v9, v18, v17
	v_fmac_f32_e32 v18, v19, v16
	v_fma_f32 v9, -v9, v18, v17
	v_div_fmas_f32 v9, v9, v16, v18
	v_div_fixup_f32 v16, v9, v10, v8
	v_cvt_pk_bf16_f32 v8, v24, v25
	v_cvt_pk_bf16_f32 v9, v14, v15
	v_cvt_pk_bf16_f32 v10, v12, v13
	v_cvt_pk_bf16_f32 v11, v16, v11
	global_store_dwordx4 v[48:49], v[8:11], off offset:32
	s_nop 0
	v_pk_fma_f32 v[0:1], v[0:1], v[168:169], v[176:177]
	v_pk_fma_f32 v[4:5], v[4:5], v[172:173], v[184:185]
	s_nop 0
	v_mul_f32_e32 v16, 0xbfb8aa3b, v4
	v_mul_f32_e32 v17, 0xbfb8aa3b, v5
	v_exp_f32_e32 v16, v16
	v_exp_f32_e32 v17, v17
	s_nop 0
	v_pk_add_f32 v[16:17], v[16:17], 1.0 op_sel_hi:[1,0]
	s_nop 0
	v_div_scale_f32 v20, s[0:1], v17, v17, v5
	v_rcp_f32_e32 v21, v20
	s_nop 0
	v_fma_f32 v24, -v20, v21, 1.0
	v_fmac_f32_e32 v21, v24, v21
	v_div_scale_f32 v24, vcc, v5, v17, v5
	v_mul_f32_e32 v25, v24, v21
	v_fma_f32 v26, -v20, v25, v24
	v_fmac_f32_e32 v25, v26, v21
	v_fma_f32 v20, -v20, v25, v24
	v_div_fmas_f32 v20, v20, v21, v25
	v_div_fixup_f32 v17, v20, v17, v5
	v_div_scale_f32 v5, s[0:1], v16, v16, v4
	v_rcp_f32_e32 v20, v5
	s_nop 0
	v_fma_f32 v21, -v5, v20, 1.0
	v_fmac_f32_e32 v20, v21, v20
	v_div_scale_f32 v21, vcc, v4, v16, v4
	v_mul_f32_e32 v24, v21, v20
	v_fma_f32 v25, -v5, v24, v21
	v_fmac_f32_e32 v24, v25, v20
	v_fma_f32 v5, -v5, v24, v21
	v_div_fmas_f32 v5, v5, v20, v24
	v_div_fixup_f32 v16, v5, v16, v4
	v_pk_add_f32 v[4:5], v[6:7], v[50:51] op_sel:[0,1] neg_lo:[0,1] neg_hi:[0,1]
	s_nop 0
	v_pk_mul_f32 v[4:5], v[4:5], v[52:53] op_sel_hi:[1,0]
	s_nop 0
	v_pk_fma_f32 v[4:5], v[4:5], v[174:175], v[186:187]
	s_nop 0
	v_mul_f32_e32 v6, 0xbfb8aa3b, v4
	v_mul_f32_e32 v7, 0xbfb8aa3b, v5
	v_exp_f32_e32 v6, v6
	v_exp_f32_e32 v7, v7
	s_nop 0
	v_pk_add_f32 v[6:7], v[6:7], 1.0 op_sel_hi:[1,0]
	s_nop 0
	v_div_scale_f32 v18, s[0:1], v7, v7, v5
	v_rcp_f32_e32 v19, v18
	s_nop 0
	v_fma_f32 v20, -v18, v19, 1.0
	v_fmac_f32_e32 v19, v20, v19
	v_div_scale_f32 v20, vcc, v5, v7, v5
	v_mul_f32_e32 v21, v20, v19
	v_fma_f32 v22, -v18, v21, v20
	v_fmac_f32_e32 v21, v22, v19
	v_fma_f32 v18, -v18, v21, v20
	v_div_fmas_f32 v18, v18, v19, v21
	v_div_fixup_f32 v7, v18, v7, v5
	v_div_scale_f32 v5, s[0:1], v6, v6, v4
	v_rcp_f32_e32 v18, v5
	s_nop 0
	v_fma_f32 v19, -v5, v18, 1.0
	v_fmac_f32_e32 v18, v19, v18
	v_div_scale_f32 v19, vcc, v4, v6, v4
	v_mul_f32_e32 v20, v19, v18
	v_fma_f32 v21, -v5, v20, v19
	v_fmac_f32_e32 v20, v21, v18
	v_fma_f32 v5, -v5, v20, v19
	v_div_fmas_f32 v5, v5, v18, v20
	v_div_fixup_f32 v6, v5, v6, v4
	v_mul_f32_e32 v4, 0xbfb8aa3b, v0
	v_mul_f32_e32 v5, 0xbfb8aa3b, v1
	v_exp_f32_e32 v4, v4
	v_exp_f32_e32 v5, v5
	s_nop 0
	v_pk_add_f32 v[4:5], v[4:5], 1.0 op_sel_hi:[1,0]
	s_nop 0
	v_div_scale_f32 v8, s[0:1], v5, v5, v1
	v_rcp_f32_e32 v9, v8
	s_nop 0
	v_fma_f32 v12, -v8, v9, 1.0
	v_fmac_f32_e32 v9, v12, v9
	v_div_scale_f32 v12, vcc, v1, v5, v1
	v_mul_f32_e32 v13, v12, v9
	v_fma_f32 v18, -v8, v13, v12
	v_fmac_f32_e32 v13, v18, v9
	v_fma_f32 v8, -v8, v13, v12
	v_div_fmas_f32 v8, v8, v9, v13
	v_div_fixup_f32 v5, v8, v5, v1
	v_div_scale_f32 v1, s[0:1], v4, v4, v0
	v_rcp_f32_e32 v8, v1
	s_nop 0
	v_fma_f32 v9, -v1, v8, 1.0
	v_fmac_f32_e32 v8, v9, v8
	v_div_scale_f32 v9, vcc, v0, v4, v0
	v_mul_f32_e32 v12, v9, v8
	v_fma_f32 v13, -v1, v12, v9
	v_fmac_f32_e32 v12, v13, v8
	v_fma_f32 v1, -v1, v12, v9
	v_div_fmas_f32 v1, v1, v8, v12
	v_div_fixup_f32 v4, v1, v4, v0
	v_pk_add_f32 v[0:1], v[2:3], v[50:51] op_sel:[0,1] neg_lo:[0,1] neg_hi:[0,1]
	s_nop 0
	v_pk_mul_f32 v[0:1], v[0:1], v[52:53] op_sel_hi:[1,0]
	s_nop 0
	v_pk_fma_f32 v[0:1], v[0:1], v[170:171], v[178:179]
	s_nop 0
	v_mul_f32_e32 v2, 0xbfb8aa3b, v0
	v_mul_f32_e32 v3, 0xbfb8aa3b, v1
	v_exp_f32_e32 v2, v2
	v_exp_f32_e32 v3, v3
	s_nop 0
	v_pk_add_f32 v[2:3], v[2:3], 1.0 op_sel_hi:[1,0]
	s_nop 0
	v_div_scale_f32 v8, s[0:1], v3, v3, v1
	v_rcp_f32_e32 v9, v8
	s_nop 0
	v_fma_f32 v10, -v8, v9, 1.0
	v_fmac_f32_e32 v9, v10, v9
	v_div_scale_f32 v10, vcc, v1, v3, v1
	v_mul_f32_e32 v11, v10, v9
	v_fma_f32 v12, -v8, v11, v10
	v_fmac_f32_e32 v11, v12, v9
	v_fma_f32 v8, -v8, v11, v10
	v_div_fmas_f32 v8, v8, v9, v11
	v_div_fixup_f32 v3, v8, v3, v1
	v_div_scale_f32 v1, s[0:1], v2, v2, v0
	v_rcp_f32_e32 v8, v1
	s_nop 0
	v_fma_f32 v9, -v1, v8, 1.0
	v_fmac_f32_e32 v8, v9, v8
	v_div_scale_f32 v9, vcc, v0, v2, v0
	v_mul_f32_e32 v10, v9, v8
	v_fma_f32 v11, -v1, v10, v9
	v_fmac_f32_e32 v10, v11, v8
	v_fma_f32 v1, -v1, v10, v9
	v_div_fmas_f32 v1, v1, v8, v10
	v_div_fixup_f32 v8, v1, v2, v0
	v_cvt_pk_bf16_f32 v0, v16, v17
	v_cvt_pk_bf16_f32 v1, v6, v7
	v_cvt_pk_bf16_f32 v2, v4, v5
	v_cvt_pk_bf16_f32 v3, v8, v3
	global_store_dwordx4 v[48:49], v[0:3], off offset:48
	s_barrier
	s_cbranch_scc0 .LBB0_858
